# v41: row-sum reductions in residual/final/qk-norm epilogues via v_permlane16_swap/v_permlane32_swap instead of two ds_bpermute round trips per row group (bit-identical sums)
# speedup vs baseline: 1.0033x; 1.0033x over previous
; __device__ __forceinline__ u32x4 pack8(const f32x4 a, const f32x4 b) { u32x4 w; w.x = cvtpk(a[0], a[1]); w.y = cvtpk(a[2], a[3]); w.z = cvtpk(b[0], b[1]); w.w = cvtpk(b[2], b[3]); return w; }
; __device__ __forceinline__ void unpack8(const u32x4 w, f32x4& a, f32x4& b) { a = (f32x4){bflo(w.x), bfhi(w.x), bflo(w.y), bfhi(w.y)}; b = (f32x4){bflo(w.z), bfhi(w.z), bflo(w.w), bfhi(w.w)}; }
;     __device__ __forceinline__ void operator()(const Acc& acc, const Unit& u, int wr, int wc, int fr, int fq) const {
;         const size_t off0 = (size_t)(u.pm * BM + wr * 64 + fr) * D + u.pn * BM + wc * 32 + 8 * fq;
;         u32x4 bw[2][4][2];
; #pragma unroll
;         for (int ai = 0; ai < 2; ++ai)
; #pragma unroll
;             for (int m = 0; m < 4; ++m)
; #pragma unroll
;                 for (int bj = 0; bj < 2; ++bj) bw[ai][m][bj] = *(const u32x4*)((const bf16_t*)base + off0 + (size_t)(ai * HALF + m * 16) * D + bj * HALF);
; #pragma unroll
;         for (int ai = 0; ai < 2; ++ai)
; #pragma unroll
;             for (int m = 0; m < 4; ++m) {
;                 const int row = u.pm * BM + ai * HALF + wr * 64 + m * 16 + fr; float s = 0.f;
; #pragma unroll
;                 for (int bj = 0; bj < 2; ++bj) {
;                     const size_t off = off0 + (size_t)(ai * HALF + m * 16) * D + bj * HALF;
;                     f32x4 b0, b1; unpack8(bw[ai][m][bj], b0, b1);
;                     const f32x4 v0 = b0 + acc[ai][bj][m][0] * scale, v1 = b1 + acc[ai][bj][m][1] * scale;
;                     s += (v0[0] * v0[0] + v0[1] * v0[1]) + (v0[2] * v0[2] + v0[3] * v0[3]) + (v1[0] * v1[0] + v1[1] * v1[1]) + (v1[2] * v1[2] + v1[3] * v1[3]);
;                     if (OUT_F32) { *(f32x4*)(outf + off) = v0; *(f32x4*)(outf + off + 4) = v1; }
;                     if (OUT_BF16) *(u32x4*)(outb + off) = pack8(v0, v1);
;                 }
;                 s += __shfl_xor(s, 16); s += __shfl_xor(s, 32);
;                 if (fq == 0) ssq[(size_t)row * 16 + u.pn * 4 + wc] = s;
.LBB0_681:
	v_lshl_add_u32 v206, s84, 8, v212
	v_ashrrev_i32_e32 v207, 31, v206
	v_readlane_b32 s88, v252, 16
	s_lshl_b32 s38, s18, 8
	v_lshlrev_b64 v[118:119], 11, v[206:207]
	v_readlane_b32 s89, v252, 17
	s_ashr_i32 s39, s38, 31
	v_and_b32_e32 v219, 64, v217
	v_lshl_add_u64 v[118:119], s[88:89], 0, v[118:119]
	v_lshl_add_u64 v[118:119], s[38:39], 1, v[118:119]
	v_lshl_add_u64 v[208:209], v[118:119], 0, v[194:195]
	global_load_dwordx4 v[220:223], v[208:209], off
	global_load_dwordx4 v[224:227], v[208:209], off offset:256
	v_add_co_u32_e32 v118, vcc, 0x8000, v208
	s_mov_b32 s38, 0x10000
	s_nop 0
	v_addc_co_u32_e32 v119, vcc, 0, v209, vcc
	v_add_co_u32_e32 v120, vcc, s38, v208
	s_mov_b32 s38, 0x18000
	s_nop 0
	v_addc_co_u32_e32 v121, vcc, 0, v209, vcc
	global_load_dwordx4 v[182:185], v[118:119], off
	global_load_dwordx4 v[178:181], v[118:119], off offset:256
	v_add_co_u32_e32 v118, vcc, s38, v208
	s_mov_b32 s38, 0x40000
	s_nop 0
	v_addc_co_u32_e32 v119, vcc, 0, v209, vcc
	global_load_dwordx4 v[174:177], v[120:121], off
	global_load_dwordx4 v[170:173], v[120:121], off offset:256
	v_add_co_u32_e32 v120, vcc, s38, v208
	s_mov_b32 s38, 0x48000
	s_nop 0
	v_addc_co_u32_e32 v121, vcc, 0, v209, vcc
	global_load_dwordx4 v[166:169], v[118:119], off
	global_load_dwordx4 v[162:165], v[118:119], off offset:256
	v_add_co_u32_e32 v118, vcc, s38, v208
	s_mov_b32 s38, 0x50000
	s_nop 0
	v_addc_co_u32_e32 v119, vcc, 0, v209, vcc
	global_load_dwordx4 v[158:161], v[120:121], off
	global_load_dwordx4 v[154:157], v[120:121], off offset:256
	v_add_co_u32_e32 v120, vcc, s38, v208
	s_mov_b32 s38, 0x58000
	s_nop 0
	v_addc_co_u32_e32 v121, vcc, 0, v209, vcc
	global_load_dwordx4 v[150:153], v[118:119], off
	global_load_dwordx4 v[146:149], v[118:119], off offset:256
	v_add_co_u32_e32 v118, vcc, s38, v208
	global_load_dwordx4 v[142:145], v[120:121], off
	global_load_dwordx4 v[138:141], v[120:121], off offset:256
	v_addc_co_u32_e32 v119, vcc, 0, v209, vcc
	global_load_dwordx4 v[126:129], v[118:119], off
	s_nop 0
	global_load_dwordx4 v[118:121], v[118:119], off offset:256
	v_xor_b32_e32 v218, 16, v217
	v_add_u32_e32 v219, 64, v219
	v_xor_b32_e32 v228, 32, v217
	v_cmp_lt_i32_e32 vcc, v218, v219
	s_lshl_b32 s38, s18, 2
	s_ashr_i32 s39, s38, 31
	v_cndmask_b32_e32 v218, v217, v218, vcc
	v_cmp_lt_i32_e32 vcc, v228, v219
	v_lshlrev_b32_e32 v219, 2, v218
	s_waitcnt vmcnt(0)
	v_and_b32_e32 v229, 0xffff0000, v220
	v_cndmask_b32_e32 v228, v217, v228, vcc
	v_lshlrev_b32_e32 v218, 2, v228
	v_lshlrev_b32_e32 v228, 16, v220
	v_lshlrev_b32_e32 v220, 16, v221
	v_and_b32_e32 v221, 0xffff0000, v221
	v_lshlrev_b32_e32 v230, 16, v222
	v_and_b32_e32 v231, 0xffff0000, v222
	v_lshlrev_b32_e32 v222, 16, v223
	v_and_b32_e32 v223, 0xffff0000, v223
	v_pk_fma_f32 v[136:137], v[136:137], 0.5, v[220:221] op_sel_hi:[1,0,1]
	v_pk_fma_f32 v[134:135], v[134:135], 0.5, v[228:229] op_sel_hi:[1,0,1]
	v_pk_fma_f32 v[220:221], v[132:133], 0.5, v[222:223] op_sel_hi:[1,0,1]
	v_pk_fma_f32 v[132:133], v[130:131], 0.5, v[230:231] op_sel_hi:[1,0,1]
	v_mul_f32_e32 v130, v135, v135
	v_mul_f32_e32 v131, v137, v137
	v_mul_f32_e32 v222, v133, v133
	v_fmac_f32_e32 v130, v134, v134
	v_fmac_f32_e32 v131, v136, v136
	v_mul_f32_e32 v223, v221, v221
	v_fmac_f32_e32 v222, v132, v132
	v_add_f32_e32 v130, v130, v131
	v_add_f32_e32 v130, v222, v130
	v_fmac_f32_e32 v223, v220, v220
	v_add_f32_e32 v228, v223, v130
	v_cvt_pk_bf16_f32 v130, v134, v135
	v_cvt_pk_bf16_f32 v131, v136, v137
	v_lshlrev_b32_e32 v134, 16, v224
	v_and_b32_e32 v135, 0xffff0000, v224
	v_lshlrev_b32_e32 v136, 16, v225
	v_and_b32_e32 v137, 0xffff0000, v225
	v_lshlrev_b32_e32 v222, 16, v226
	v_and_b32_e32 v223, 0xffff0000, v226
	v_pk_fma_f32 v[124:125], v[124:125], 0.5, v[136:137] op_sel_hi:[1,0,1]
	v_pk_fma_f32 v[122:123], v[122:123], 0.5, v[134:135] op_sel_hi:[1,0,1]
	v_pk_fma_f32 v[134:135], v[114:115], 0.5, v[222:223] op_sel_hi:[1,0,1]
	v_mul_f32_e32 v114, v123, v123
	v_mul_f32_e32 v115, v125, v125
	v_fmac_f32_e32 v114, v122, v122
	v_fmac_f32_e32 v115, v124, v124
	v_lshlrev_b32_e32 v224, 16, v227
	v_and_b32_e32 v225, 0xffff0000, v227
	v_add_f32_e32 v114, v114, v115
	v_mul_f32_e32 v115, v135, v135
	v_pk_fma_f32 v[116:117], v[116:117], 0.5, v[224:225] op_sel_hi:[1,0,1]
	v_fmac_f32_e32 v115, v134, v134
	v_add_f32_e32 v114, v115, v114
	v_mul_f32_e32 v115, v117, v117
	v_fmac_f32_e32 v115, v116, v116
	v_add_f32_e32 v114, v115, v114
	v_add_f32_e32 v114, v228, v114
	v_mov_b32_e32 v115, v114
	s_nop 1
	v_permlane16_swap_b32_e32 v114, v115
	v_cvt_pk_bf16_f32 v132, v132, v133
	v_cvt_pk_bf16_f32 v133, v220, v221
	v_cvt_pk_bf16_f32 v122, v122, v123
	v_cvt_pk_bf16_f32 v123, v124, v125
	s_waitcnt lgkmcnt(0)
	v_add_f32_e32 v114, v114, v115
	v_mov_b32_e32 v115, v114
	s_nop 1
	v_permlane32_swap_b32_e32 v114, v115
	v_cvt_pk_bf16_f32 v124, v134, v135
	v_cvt_pk_bf16_f32 v125, v116, v117
	global_store_dwordx4 v[208:209], v[130:133], off
	global_store_dwordx4 v[208:209], v[122:125], off offset:256
	s_and_saveexec_b64 s[40:41], s[4:5]
	s_cbranch_execz .LBB0_683
	v_lshlrev_b64 v[116:117], 6, v[206:207]
	v_lshl_add_u64 v[116:117], s[22:23], 0, v[116:117]
	v_lshl_add_u64 v[116:117], s[38:39], 2, v[116:117]
	s_lshl_b32 s18, s55, 2
	v_lshl_add_u64 v[116:117], v[116:117], 0, s[18:19]
	s_waitcnt lgkmcnt(0)
	v_add_f32_e32 v114, v114, v115
	global_store_dword v[116:117], v114, off
; __device__ __forceinline__ u32x4 pack8(const f32x4 a, const f32x4 b) { u32x4 w; w.x = cvtpk(a[0], a[1]); w.y = cvtpk(a[2], a[3]); w.z = cvtpk(b[0], b[1]); w.w = cvtpk(b[2], b[3]); return w; }
; __device__ __forceinline__ void unpack8(const u32x4 w, f32x4& a, f32x4& b) { a = (f32x4){bflo(w.x), bfhi(w.x), bflo(w.y), bfhi(w.y)}; b = (f32x4){bflo(w.z), bfhi(w.z), bflo(w.w), bfhi(w.w)}; }
;     __device__ __forceinline__ void operator()(const Acc& acc, const Unit& u, int wr, int wc, int fr, int fq) const {
;     ...
;         for (int ai = 0; ai < 2; ++ai)
; #pragma unroll
;             for (int m = 0; m < 4; ++m) {
;                 const int row = u.pm * BM + ai * HALF + wr * 64 + m * 16 + fr; float s = 0.f;
; #pragma unroll
;                 for (int bj = 0; bj < 2; ++bj) {
;                     const size_t off = off0 + (size_t)(ai * HALF + m * 16) * D + bj * HALF;
;                     f32x4 b0, b1; unpack8(bw[ai][m][bj], b0, b1);
;                     const f32x4 v0 = b0 + acc[ai][bj][m][0] * scale, v1 = b1 + acc[ai][bj][m][1] * scale;
;                     s += (v0[0] * v0[0] + v0[1] * v0[1]) + (v0[2] * v0[2] + v0[3] * v0[3]) + (v1[0] * v1[0] + v1[1] * v1[1]) + (v1[2] * v1[2] + v1[3] * v1[3]);
;                     if (OUT_F32) { *(f32x4*)(outf + off) = v0; *(f32x4*)(outf + off + 4) = v1; }
;                     if (OUT_BF16) *(u32x4*)(outb + off) = pack8(v0, v1);
;                 }
;                 s += __shfl_xor(s, 16); s += __shfl_xor(s, 32);
;                 if (fq == 0) ssq[(size_t)row * 16 + u.pn * 4 + wc] = s;
.LBB0_683:
	s_or_b64 exec, exec, s[40:41]
	v_lshlrev_b32_e32 v122, 16, v182
	v_and_b32_e32 v123, 0xffff0000, v182
	v_lshlrev_b32_e32 v124, 16, v183
	v_and_b32_e32 v125, 0xffff0000, v183
	v_lshlrev_b32_e32 v130, 16, v184
	v_and_b32_e32 v131, 0xffff0000, v184
	v_lshlrev_b32_e32 v132, 16, v185
	v_and_b32_e32 v133, 0xffff0000, v185
	v_pk_fma_f32 v[112:113], v[112:113], 0.5, v[124:125] op_sel_hi:[1,0,1]
	v_pk_fma_f32 v[110:111], v[110:111], 0.5, v[122:123] op_sel_hi:[1,0,1]
	v_pk_fma_f32 v[122:123], v[108:109], 0.5, v[132:133] op_sel_hi:[1,0,1]
	v_pk_fma_f32 v[108:109], v[106:107], 0.5, v[130:131] op_sel_hi:[1,0,1]
	v_mul_f32_e32 v106, v111, v111
	v_mul_f32_e32 v107, v113, v113
	v_fmac_f32_e32 v106, v110, v110
	v_fmac_f32_e32 v107, v112, v112
	v_add_f32_e32 v106, v106, v107
	v_mul_f32_e32 v107, v109, v109
	v_fmac_f32_e32 v107, v108, v108
	v_add_f32_e32 v106, v107, v106
	v_mul_f32_e32 v107, v123, v123
	v_fmac_f32_e32 v107, v122, v122
	v_add_f32_e32 v132, v107, v106
	v_cvt_pk_bf16_f32 v106, v110, v111
	v_cvt_pk_bf16_f32 v107, v112, v113
	v_lshlrev_b32_e32 v110, 16, v178
	v_and_b32_e32 v111, 0xffff0000, v178
	v_lshlrev_b32_e32 v112, 16, v179
	v_and_b32_e32 v113, 0xffff0000, v179
	v_lshlrev_b32_e32 v124, 16, v180
	v_and_b32_e32 v125, 0xffff0000, v180
	v_pk_fma_f32 v[104:105], v[104:105], 0.5, v[112:113] op_sel_hi:[1,0,1]
	v_pk_fma_f32 v[102:103], v[102:103], 0.5, v[110:111] op_sel_hi:[1,0,1]
	v_pk_fma_f32 v[112:113], v[98:99], 0.5, v[124:125] op_sel_hi:[1,0,1]
	v_mul_f32_e32 v98, v103, v103
	v_mul_f32_e32 v99, v105, v105
	v_fmac_f32_e32 v98, v102, v102
	v_fmac_f32_e32 v99, v104, v104
	v_lshlrev_b32_e32 v130, 16, v181
	v_and_b32_e32 v131, 0xffff0000, v181
	v_add_f32_e32 v98, v98, v99
	v_mul_f32_e32 v99, v113, v113
	v_pk_fma_f32 v[110:111], v[100:101], 0.5, v[130:131] op_sel_hi:[1,0,1]
	v_fmac_f32_e32 v99, v112, v112
	v_add_f32_e32 v98, v99, v98
	v_mul_f32_e32 v99, v111, v111
	v_fmac_f32_e32 v99, v110, v110
	v_add_f32_e32 v98, v99, v98
	v_add_f32_e32 v98, v132, v98
	v_mov_b32_e32 v99, v98
	s_nop 1
	v_permlane16_swap_b32_e32 v98, v99
	s_mov_b64 s[40:41], 0x8000
	s_waitcnt lgkmcnt(1)
	v_lshl_add_u64 v[114:115], v[208:209], 0, s[40:41]
	s_mov_b64 s[40:41], 0x8100
	v_lshl_add_u64 v[116:117], v[208:209], 0, s[40:41]
	s_waitcnt lgkmcnt(0)
	v_add_f32_e32 v98, v98, v99
	v_mov_b32_e32 v99, v98
	s_nop 1
	v_permlane32_swap_b32_e32 v98, v99
	v_cvt_pk_bf16_f32 v108, v108, v109
	v_cvt_pk_bf16_f32 v109, v122, v123
	v_cvt_pk_bf16_f32 v100, v102, v103
	v_cvt_pk_bf16_f32 v101, v104, v105
	v_cvt_pk_bf16_f32 v102, v112, v113
	v_cvt_pk_bf16_f32 v103, v110, v111
	global_store_dwordx4 v[114:115], v[106:109], off
	global_store_dwordx4 v[116:117], v[100:103], off
	s_and_saveexec_b64 s[40:41], s[4:5]
	s_cbranch_execz .LBB0_685
	v_or_b32_e32 v100, 16, v206
	v_ashrrev_i32_e32 v101, 31, v100
	s_waitcnt lgkmcnt(0)
	v_add_f32_e32 v102, v98, v99
	v_lshlrev_b64 v[98:99], 6, v[100:101]
	v_lshl_add_u64 v[98:99], s[22:23], 0, v[98:99]
	v_lshl_add_u64 v[98:99], s[38:39], 2, v[98:99]
	s_lshl_b32 s18, s55, 2
	v_lshl_add_u64 v[98:99], v[98:99], 0, s[18:19]
	global_store_dword v[98:99], v102, off
.LBB0_685:
	s_or_b64 exec, exec, s[40:41]
	v_lshlrev_b32_e32 v102, 16, v174
	v_and_b32_e32 v103, 0xffff0000, v174
	v_lshlrev_b32_e32 v104, 16, v175
	v_and_b32_e32 v105, 0xffff0000, v175
	v_lshlrev_b32_e32 v106, 16, v176
	v_and_b32_e32 v107, 0xffff0000, v176
	v_lshlrev_b32_e32 v108, 16, v177
	v_and_b32_e32 v109, 0xffff0000, v177
	v_pk_fma_f32 v[96:97], v[96:97], 0.5, v[104:105] op_sel_hi:[1,0,1]
	v_pk_fma_f32 v[94:95], v[94:95], 0.5, v[102:103] op_sel_hi:[1,0,1]
	v_pk_fma_f32 v[102:103], v[92:93], 0.5, v[108:109] op_sel_hi:[1,0,1]
	v_pk_fma_f32 v[92:93], v[90:91], 0.5, v[106:107] op_sel_hi:[1,0,1]
	v_mul_f32_e32 v90, v95, v95
	v_mul_f32_e32 v91, v97, v97
	v_fmac_f32_e32 v90, v94, v94
	v_fmac_f32_e32 v91, v96, v96
	v_add_f32_e32 v90, v90, v91
	v_mul_f32_e32 v91, v93, v93
	v_fmac_f32_e32 v91, v92, v92
	v_add_f32_e32 v90, v91, v90
	v_mul_f32_e32 v91, v103, v103
	v_fmac_f32_e32 v91, v102, v102
	v_add_f32_e32 v108, v91, v90
	v_cvt_pk_bf16_f32 v90, v94, v95
	v_cvt_pk_bf16_f32 v91, v96, v97
	v_lshlrev_b32_e32 v94, 16, v170
	v_and_b32_e32 v95, 0xffff0000, v170
	v_lshlrev_b32_e32 v96, 16, v171
	v_and_b32_e32 v97, 0xffff0000, v171
	v_lshlrev_b32_e32 v104, 16, v172
	v_and_b32_e32 v105, 0xffff0000, v172
	v_pk_fma_f32 v[88:89], v[88:89], 0.5, v[96:97] op_sel_hi:[1,0,1]
	v_pk_fma_f32 v[86:87], v[86:87], 0.5, v[94:95] op_sel_hi:[1,0,1]
	v_pk_fma_f32 v[96:97], v[82:83], 0.5, v[104:105] op_sel_hi:[1,0,1]
	v_mul_f32_e32 v82, v87, v87
	v_mul_f32_e32 v83, v89, v89
	v_fmac_f32_e32 v82, v86, v86
	v_fmac_f32_e32 v83, v88, v88
	v_lshlrev_b32_e32 v106, 16, v173
	v_and_b32_e32 v107, 0xffff0000, v173
	v_add_f32_e32 v82, v82, v83
	v_mul_f32_e32 v83, v97, v97
	v_pk_fma_f32 v[94:95], v[84:85], 0.5, v[106:107] op_sel_hi:[1,0,1]
	v_fmac_f32_e32 v83, v96, v96
	v_add_f32_e32 v82, v83, v82
	v_mul_f32_e32 v83, v95, v95
	v_fmac_f32_e32 v83, v94, v94
	v_add_f32_e32 v82, v83, v82
	v_add_f32_e32 v82, v108, v82
	v_mov_b32_e32 v83, v82
	s_nop 1
	v_permlane16_swap_b32_e32 v82, v83
	s_mov_b64 s[40:41], 0x10000
	s_waitcnt lgkmcnt(1)
	v_lshl_add_u64 v[98:99], v[208:209], 0, s[40:41]
	s_mov_b64 s[40:41], 0x10100
	v_lshl_add_u64 v[100:101], v[208:209], 0, s[40:41]
	s_waitcnt lgkmcnt(0)
	v_add_f32_e32 v82, v82, v83
	v_mov_b32_e32 v83, v82
	s_nop 1
	v_permlane32_swap_b32_e32 v82, v83
	v_cvt_pk_bf16_f32 v92, v92, v93
	v_cvt_pk_bf16_f32 v93, v102, v103
	v_cvt_pk_bf16_f32 v84, v86, v87
	v_cvt_pk_bf16_f32 v85, v88, v89
	v_cvt_pk_bf16_f32 v86, v96, v97
	v_cvt_pk_bf16_f32 v87, v94, v95
	global_store_dwordx4 v[98:99], v[90:93], off
	global_store_dwordx4 v[100:101], v[84:87], off
	s_and_saveexec_b64 s[40:41], s[4:5]
	s_cbranch_execz .LBB0_687
	v_or_b32_e32 v84, 32, v206
	v_ashrrev_i32_e32 v85, 31, v84
	s_waitcnt lgkmcnt(0)
	v_add_f32_e32 v86, v82, v83
	v_lshlrev_b64 v[82:83], 6, v[84:85]
	v_lshl_add_u64 v[82:83], s[22:23], 0, v[82:83]
	v_lshl_add_u64 v[82:83], s[38:39], 2, v[82:83]
	s_lshl_b32 s18, s55, 2
	v_lshl_add_u64 v[82:83], v[82:83], 0, s[18:19]
	global_store_dword v[82:83], v86, off
; __device__ __forceinline__ u32x4 pack8(const f32x4 a, const f32x4 b) { u32x4 w; w.x = cvtpk(a[0], a[1]); w.y = cvtpk(a[2], a[3]); w.z = cvtpk(b[0], b[1]); w.w = cvtpk(b[2], b[3]); return w; }
; __device__ __forceinline__ void unpack8(const u32x4 w, f32x4& a, f32x4& b) { a = (f32x4){bflo(w.x), bfhi(w.x), bflo(w.y), bfhi(w.y)}; b = (f32x4){bflo(w.z), bfhi(w.z), bflo(w.w), bfhi(w.w)}; }
;     __device__ __forceinline__ void operator()(const Acc& acc, const Unit& u, int wr, int wc, int fr, int fq) const {
;     ...
;         for (int ai = 0; ai < 2; ++ai)
; #pragma unroll
;             for (int m = 0; m < 4; ++m) {
;                 const int row = u.pm * BM + ai * HALF + wr * 64 + m * 16 + fr; float s = 0.f;
; #pragma unroll
;                 for (int bj = 0; bj < 2; ++bj) {
;                     const size_t off = off0 + (size_t)(ai * HALF + m * 16) * D + bj * HALF;
;                     f32x4 b0, b1; unpack8(bw[ai][m][bj], b0, b1);
;                     const f32x4 v0 = b0 + acc[ai][bj][m][0] * scale, v1 = b1 + acc[ai][bj][m][1] * scale;
;                     s += (v0[0] * v0[0] + v0[1] * v0[1]) + (v0[2] * v0[2] + v0[3] * v0[3]) + (v1[0] * v1[0] + v1[1] * v1[1]) + (v1[2] * v1[2] + v1[3] * v1[3]);
;                     if (OUT_F32) { *(f32x4*)(outf + off) = v0; *(f32x4*)(outf + off + 4) = v1; }
;                     if (OUT_BF16) *(u32x4*)(outb + off) = pack8(v0, v1);
;                 }
;                 s += __shfl_xor(s, 16); s += __shfl_xor(s, 32);
;                 if (fq == 0) ssq[(size_t)row * 16 + u.pn * 4 + wc] = s;
.LBB0_687:
	s_or_b64 exec, exec, s[40:41]
	v_lshlrev_b32_e32 v86, 16, v166
	v_and_b32_e32 v87, 0xffff0000, v166
	v_lshlrev_b32_e32 v88, 16, v167
	v_and_b32_e32 v89, 0xffff0000, v167
	v_lshlrev_b32_e32 v90, 16, v168
	v_and_b32_e32 v91, 0xffff0000, v168
	v_lshlrev_b32_e32 v92, 16, v169
	v_and_b32_e32 v93, 0xffff0000, v169
	v_pk_fma_f32 v[80:81], v[80:81], 0.5, v[88:89] op_sel_hi:[1,0,1]
	v_pk_fma_f32 v[78:79], v[78:79], 0.5, v[86:87] op_sel_hi:[1,0,1]
	v_pk_fma_f32 v[86:87], v[76:77], 0.5, v[92:93] op_sel_hi:[1,0,1]
	v_pk_fma_f32 v[76:77], v[74:75], 0.5, v[90:91] op_sel_hi:[1,0,1]
	v_mul_f32_e32 v74, v79, v79
	v_mul_f32_e32 v75, v81, v81
	v_fmac_f32_e32 v74, v78, v78
	v_fmac_f32_e32 v75, v80, v80
	v_add_f32_e32 v74, v74, v75
	v_mul_f32_e32 v75, v77, v77
	v_fmac_f32_e32 v75, v76, v76
	v_add_f32_e32 v74, v75, v74
	v_mul_f32_e32 v75, v87, v87
	v_fmac_f32_e32 v75, v86, v86
	v_add_f32_e32 v92, v75, v74
	v_cvt_pk_bf16_f32 v74, v78, v79
	v_cvt_pk_bf16_f32 v75, v80, v81
	v_lshlrev_b32_e32 v78, 16, v162
	v_and_b32_e32 v79, 0xffff0000, v162
	v_lshlrev_b32_e32 v80, 16, v163
	v_and_b32_e32 v81, 0xffff0000, v163
	v_lshlrev_b32_e32 v88, 16, v164
	v_and_b32_e32 v89, 0xffff0000, v164
	v_pk_fma_f32 v[72:73], v[72:73], 0.5, v[80:81] op_sel_hi:[1,0,1]
	v_pk_fma_f32 v[70:71], v[70:71], 0.5, v[78:79] op_sel_hi:[1,0,1]
	v_pk_fma_f32 v[80:81], v[66:67], 0.5, v[88:89] op_sel_hi:[1,0,1]
	v_mul_f32_e32 v66, v71, v71
	v_mul_f32_e32 v67, v73, v73
	v_fmac_f32_e32 v66, v70, v70
	v_fmac_f32_e32 v67, v72, v72
	v_lshlrev_b32_e32 v90, 16, v165
	v_and_b32_e32 v91, 0xffff0000, v165
	v_add_f32_e32 v66, v66, v67
	v_mul_f32_e32 v67, v81, v81
	v_pk_fma_f32 v[78:79], v[68:69], 0.5, v[90:91] op_sel_hi:[1,0,1]
	v_fmac_f32_e32 v67, v80, v80
	v_add_f32_e32 v66, v67, v66
	v_mul_f32_e32 v67, v79, v79
	v_fmac_f32_e32 v67, v78, v78
	v_add_f32_e32 v66, v67, v66
	v_add_f32_e32 v66, v92, v66
	v_mov_b32_e32 v67, v66
	s_nop 1
	v_permlane16_swap_b32_e32 v66, v67
	s_mov_b64 s[40:41], 0x18000
	s_waitcnt lgkmcnt(1)
	v_lshl_add_u64 v[82:83], v[208:209], 0, s[40:41]
	s_mov_b64 s[40:41], 0x18100
	v_lshl_add_u64 v[84:85], v[208:209], 0, s[40:41]
	s_waitcnt lgkmcnt(0)
	v_add_f32_e32 v66, v66, v67
	v_mov_b32_e32 v67, v66
	s_nop 1
	v_permlane32_swap_b32_e32 v66, v67
	v_cvt_pk_bf16_f32 v76, v76, v77
	v_cvt_pk_bf16_f32 v77, v86, v87
	v_cvt_pk_bf16_f32 v68, v70, v71
	v_cvt_pk_bf16_f32 v69, v72, v73
	v_cvt_pk_bf16_f32 v70, v80, v81
	v_cvt_pk_bf16_f32 v71, v78, v79
	global_store_dwordx4 v[82:83], v[74:77], off
	global_store_dwordx4 v[84:85], v[68:71], off
	s_and_saveexec_b64 s[40:41], s[4:5]
	s_cbranch_execz .LBB0_689
	v_or_b32_e32 v68, 48, v206
	v_ashrrev_i32_e32 v69, 31, v68
	s_waitcnt lgkmcnt(0)
	v_add_f32_e32 v70, v66, v67
	v_lshlrev_b64 v[66:67], 6, v[68:69]
	v_lshl_add_u64 v[66:67], s[22:23], 0, v[66:67]
	v_lshl_add_u64 v[66:67], s[38:39], 2, v[66:67]
	s_lshl_b32 s18, s55, 2
	v_lshl_add_u64 v[66:67], v[66:67], 0, s[18:19]
	global_store_dword v[66:67], v70, off
.LBB0_689:
	s_or_b64 exec, exec, s[40:41]
	v_lshlrev_b32_e32 v70, 16, v158
	v_and_b32_e32 v71, 0xffff0000, v158
	v_lshlrev_b32_e32 v72, 16, v159
	v_and_b32_e32 v73, 0xffff0000, v159
	v_lshlrev_b32_e32 v74, 16, v160
	v_and_b32_e32 v75, 0xffff0000, v160
	v_lshlrev_b32_e32 v76, 16, v161
	v_and_b32_e32 v77, 0xffff0000, v161
	v_pk_fma_f32 v[64:65], v[64:65], 0.5, v[72:73] op_sel_hi:[1,0,1]
	v_pk_fma_f32 v[62:63], v[62:63], 0.5, v[70:71] op_sel_hi:[1,0,1]
	v_pk_fma_f32 v[70:71], v[60:61], 0.5, v[76:77] op_sel_hi:[1,0,1]
	v_pk_fma_f32 v[60:61], v[58:59], 0.5, v[74:75] op_sel_hi:[1,0,1]
	v_mul_f32_e32 v58, v63, v63
	v_mul_f32_e32 v59, v65, v65
	v_fmac_f32_e32 v58, v62, v62
	v_fmac_f32_e32 v59, v64, v64
	v_add_f32_e32 v58, v58, v59
	v_mul_f32_e32 v59, v61, v61
	v_fmac_f32_e32 v59, v60, v60
	v_add_f32_e32 v58, v59, v58
	v_mul_f32_e32 v59, v71, v71
	v_fmac_f32_e32 v59, v70, v70
	v_add_f32_e32 v76, v59, v58
	v_cvt_pk_bf16_f32 v58, v62, v63
	v_cvt_pk_bf16_f32 v59, v64, v65
	v_lshlrev_b32_e32 v62, 16, v154
	v_and_b32_e32 v63, 0xffff0000, v154
	v_lshlrev_b32_e32 v64, 16, v155
	v_and_b32_e32 v65, 0xffff0000, v155
	v_lshlrev_b32_e32 v72, 16, v156
	v_and_b32_e32 v73, 0xffff0000, v156
	v_pk_fma_f32 v[56:57], v[56:57], 0.5, v[64:65] op_sel_hi:[1,0,1]
	v_pk_fma_f32 v[54:55], v[54:55], 0.5, v[62:63] op_sel_hi:[1,0,1]
	v_pk_fma_f32 v[64:65], v[50:51], 0.5, v[72:73] op_sel_hi:[1,0,1]
	v_mul_f32_e32 v50, v55, v55
	v_mul_f32_e32 v51, v57, v57
	v_fmac_f32_e32 v50, v54, v54
	v_fmac_f32_e32 v51, v56, v56
	v_lshlrev_b32_e32 v74, 16, v157
	v_and_b32_e32 v75, 0xffff0000, v157
	v_add_f32_e32 v50, v50, v51
	v_mul_f32_e32 v51, v65, v65
	v_pk_fma_f32 v[62:63], v[52:53], 0.5, v[74:75] op_sel_hi:[1,0,1]
	v_fmac_f32_e32 v51, v64, v64
	v_add_f32_e32 v50, v51, v50
	v_mul_f32_e32 v51, v63, v63
	v_fmac_f32_e32 v51, v62, v62
	v_add_f32_e32 v50, v51, v50
	v_add_f32_e32 v50, v76, v50
	v_mov_b32_e32 v51, v50
	s_nop 1
	v_permlane16_swap_b32_e32 v50, v51
	s_mov_b64 s[40:41], 0x40000
	s_waitcnt lgkmcnt(1)
	v_lshl_add_u64 v[66:67], v[208:209], 0, s[40:41]
	s_mov_b64 s[40:41], 0x40100
	v_lshl_add_u64 v[68:69], v[208:209], 0, s[40:41]
	s_waitcnt lgkmcnt(0)
	v_add_f32_e32 v50, v50, v51
	v_mov_b32_e32 v51, v50
	s_nop 1
	v_permlane32_swap_b32_e32 v50, v51
	v_cvt_pk_bf16_f32 v60, v60, v61
	v_cvt_pk_bf16_f32 v61, v70, v71
	v_cvt_pk_bf16_f32 v52, v54, v55
	v_cvt_pk_bf16_f32 v53, v56, v57
	v_cvt_pk_bf16_f32 v54, v64, v65
	v_cvt_pk_bf16_f32 v55, v62, v63
	global_store_dwordx4 v[66:67], v[58:61], off
	global_store_dwordx4 v[68:69], v[52:55], off
	s_and_saveexec_b64 s[40:41], s[4:5]
	s_cbranch_execz .LBB0_691
	v_add_u32_e32 v52, 0x80, v206
	v_ashrrev_i32_e32 v53, 31, v52
	s_waitcnt lgkmcnt(0)
	v_add_f32_e32 v54, v50, v51
	v_lshlrev_b64 v[50:51], 6, v[52:53]
	v_lshl_add_u64 v[50:51], s[22:23], 0, v[50:51]
	v_lshl_add_u64 v[50:51], s[38:39], 2, v[50:51]
	s_lshl_b32 s18, s55, 2
	v_lshl_add_u64 v[50:51], v[50:51], 0, s[18:19]
	global_store_dword v[50:51], v54, off
; __device__ __forceinline__ u32x4 pack8(const f32x4 a, const f32x4 b) { u32x4 w; w.x = cvtpk(a[0], a[1]); w.y = cvtpk(a[2], a[3]); w.z = cvtpk(b[0], b[1]); w.w = cvtpk(b[2], b[3]); return w; }
; __device__ __forceinline__ void unpack8(const u32x4 w, f32x4& a, f32x4& b) { a = (f32x4){bflo(w.x), bfhi(w.x), bflo(w.y), bfhi(w.y)}; b = (f32x4){bflo(w.z), bfhi(w.z), bflo(w.w), bfhi(w.w)}; }
;     __device__ __forceinline__ void operator()(const Acc& acc, const Unit& u, int wr, int wc, int fr, int fq) const {
;     ...
;         for (int ai = 0; ai < 2; ++ai)
; #pragma unroll
;             for (int m = 0; m < 4; ++m) {
;                 const int row = u.pm * BM + ai * HALF + wr * 64 + m * 16 + fr; float s = 0.f;
; #pragma unroll
;                 for (int bj = 0; bj < 2; ++bj) {
;                     const size_t off = off0 + (size_t)(ai * HALF + m * 16) * D + bj * HALF;
;                     f32x4 b0, b1; unpack8(bw[ai][m][bj], b0, b1);
;                     const f32x4 v0 = b0 + acc[ai][bj][m][0] * scale, v1 = b1 + acc[ai][bj][m][1] * scale;
;                     s += (v0[0] * v0[0] + v0[1] * v0[1]) + (v0[2] * v0[2] + v0[3] * v0[3]) + (v1[0] * v1[0] + v1[1] * v1[1]) + (v1[2] * v1[2] + v1[3] * v1[3]);
;                     if (OUT_F32) { *(f32x4*)(outf + off) = v0; *(f32x4*)(outf + off + 4) = v1; }
;                     if (OUT_BF16) *(u32x4*)(outb + off) = pack8(v0, v1);
;                 }
;                 s += __shfl_xor(s, 16); s += __shfl_xor(s, 32);
;                 if (fq == 0) ssq[(size_t)row * 16 + u.pn * 4 + wc] = s;
.LBB0_691:
	s_or_b64 exec, exec, s[40:41]
	v_lshlrev_b32_e32 v54, 16, v150
	v_and_b32_e32 v55, 0xffff0000, v150
	v_lshlrev_b32_e32 v56, 16, v151
	v_and_b32_e32 v57, 0xffff0000, v151
	v_lshlrev_b32_e32 v58, 16, v152
	v_and_b32_e32 v59, 0xffff0000, v152
	v_lshlrev_b32_e32 v60, 16, v153
	v_and_b32_e32 v61, 0xffff0000, v153
	v_pk_fma_f32 v[48:49], v[48:49], 0.5, v[56:57] op_sel_hi:[1,0,1]
	v_pk_fma_f32 v[46:47], v[46:47], 0.5, v[54:55] op_sel_hi:[1,0,1]
	v_pk_fma_f32 v[54:55], v[44:45], 0.5, v[60:61] op_sel_hi:[1,0,1]
	v_pk_fma_f32 v[44:45], v[42:43], 0.5, v[58:59] op_sel_hi:[1,0,1]
	v_mul_f32_e32 v42, v47, v47
	v_mul_f32_e32 v43, v49, v49
	v_fmac_f32_e32 v42, v46, v46
	v_fmac_f32_e32 v43, v48, v48
	v_add_f32_e32 v42, v42, v43
	v_mul_f32_e32 v43, v45, v45
	v_fmac_f32_e32 v43, v44, v44
	v_add_f32_e32 v42, v43, v42
	v_mul_f32_e32 v43, v55, v55
	v_fmac_f32_e32 v43, v54, v54
	v_add_f32_e32 v60, v43, v42
	v_cvt_pk_bf16_f32 v42, v46, v47
	v_cvt_pk_bf16_f32 v43, v48, v49
	v_lshlrev_b32_e32 v46, 16, v146
	v_and_b32_e32 v47, 0xffff0000, v146
	v_lshlrev_b32_e32 v48, 16, v147
	v_and_b32_e32 v49, 0xffff0000, v147
	v_lshlrev_b32_e32 v56, 16, v148
	v_and_b32_e32 v57, 0xffff0000, v148
	v_pk_fma_f32 v[40:41], v[40:41], 0.5, v[48:49] op_sel_hi:[1,0,1]
	v_pk_fma_f32 v[38:39], v[38:39], 0.5, v[46:47] op_sel_hi:[1,0,1]
	v_pk_fma_f32 v[48:49], v[34:35], 0.5, v[56:57] op_sel_hi:[1,0,1]
	v_mul_f32_e32 v34, v39, v39
	v_mul_f32_e32 v35, v41, v41
	v_fmac_f32_e32 v34, v38, v38
	v_fmac_f32_e32 v35, v40, v40
	v_lshlrev_b32_e32 v58, 16, v149
	v_and_b32_e32 v59, 0xffff0000, v149
	v_add_f32_e32 v34, v34, v35
	v_mul_f32_e32 v35, v49, v49
	v_pk_fma_f32 v[46:47], v[36:37], 0.5, v[58:59] op_sel_hi:[1,0,1]
	v_fmac_f32_e32 v35, v48, v48
	v_add_f32_e32 v34, v35, v34
	v_mul_f32_e32 v35, v47, v47
	v_fmac_f32_e32 v35, v46, v46
	v_add_f32_e32 v34, v35, v34
	v_add_f32_e32 v34, v60, v34
	v_mov_b32_e32 v35, v34
	s_nop 1
	v_permlane16_swap_b32_e32 v34, v35
	s_mov_b64 s[40:41], 0x48000
	s_waitcnt lgkmcnt(1)
	v_lshl_add_u64 v[50:51], v[208:209], 0, s[40:41]
	s_mov_b64 s[40:41], 0x48100
	v_lshl_add_u64 v[52:53], v[208:209], 0, s[40:41]
	s_waitcnt lgkmcnt(0)
	v_add_f32_e32 v34, v34, v35
	v_mov_b32_e32 v35, v34
	s_nop 1
	v_permlane32_swap_b32_e32 v34, v35
	v_cvt_pk_bf16_f32 v44, v44, v45
	v_cvt_pk_bf16_f32 v45, v54, v55
	v_cvt_pk_bf16_f32 v36, v38, v39
	v_cvt_pk_bf16_f32 v37, v40, v41
	v_cvt_pk_bf16_f32 v38, v48, v49
	v_cvt_pk_bf16_f32 v39, v46, v47
	global_store_dwordx4 v[50:51], v[42:45], off
	global_store_dwordx4 v[52:53], v[36:39], off
	s_and_saveexec_b64 s[40:41], s[4:5]
	s_cbranch_execz .LBB0_693
	v_add_u32_e32 v36, 0x90, v206
	v_ashrrev_i32_e32 v37, 31, v36
	s_waitcnt lgkmcnt(0)
	v_add_f32_e32 v38, v34, v35
	v_lshlrev_b64 v[34:35], 6, v[36:37]
	v_lshl_add_u64 v[34:35], s[22:23], 0, v[34:35]
	v_lshl_add_u64 v[34:35], s[38:39], 2, v[34:35]
	s_lshl_b32 s18, s55, 2
	v_lshl_add_u64 v[34:35], v[34:35], 0, s[18:19]
	global_store_dword v[34:35], v38, off
; __device__ __forceinline__ u32x4 pack8(const f32x4 a, const f32x4 b) { u32x4 w; w.x = cvtpk(a[0], a[1]); w.y = cvtpk(a[2], a[3]); w.z = cvtpk(b[0], b[1]); w.w = cvtpk(b[2], b[3]); return w; }
; __device__ __forceinline__ void unpack8(const u32x4 w, f32x4& a, f32x4& b) { a = (f32x4){bflo(w.x), bfhi(w.x), bflo(w.y), bfhi(w.y)}; b = (f32x4){bflo(w.z), bfhi(w.z), bflo(w.w), bfhi(w.w)}; }
;     __device__ __forceinline__ void operator()(const Acc& acc, const Unit& u, int wr, int wc, int fr, int fq) const {
;     ...
;         for (int ai = 0; ai < 2; ++ai)
; #pragma unroll
;             for (int m = 0; m < 4; ++m) {
;                 const int row = u.pm * BM + ai * HALF + wr * 64 + m * 16 + fr; float s = 0.f;
; #pragma unroll
;                 for (int bj = 0; bj < 2; ++bj) {
;                     const size_t off = off0 + (size_t)(ai * HALF + m * 16) * D + bj * HALF;
;                     f32x4 b0, b1; unpack8(bw[ai][m][bj], b0, b1);
;                     const f32x4 v0 = b0 + acc[ai][bj][m][0] * scale, v1 = b1 + acc[ai][bj][m][1] * scale;
;                     s += (v0[0] * v0[0] + v0[1] * v0[1]) + (v0[2] * v0[2] + v0[3] * v0[3]) + (v1[0] * v1[0] + v1[1] * v1[1]) + (v1[2] * v1[2] + v1[3] * v1[3]);
;                     if (OUT_F32) { *(f32x4*)(outf + off) = v0; *(f32x4*)(outf + off + 4) = v1; }
;                     if (OUT_BF16) *(u32x4*)(outb + off) = pack8(v0, v1);
;                 }
;                 s += __shfl_xor(s, 16); s += __shfl_xor(s, 32);
;                 if (fq == 0) ssq[(size_t)row * 16 + u.pn * 4 + wc] = s;
.LBB0_693:
	s_or_b64 exec, exec, s[40:41]
	v_lshlrev_b32_e32 v38, 16, v142
	v_and_b32_e32 v39, 0xffff0000, v142
	v_lshlrev_b32_e32 v40, 16, v143
	v_and_b32_e32 v41, 0xffff0000, v143
	v_lshlrev_b32_e32 v42, 16, v144
	v_and_b32_e32 v43, 0xffff0000, v144
	v_lshlrev_b32_e32 v44, 16, v145
	v_and_b32_e32 v45, 0xffff0000, v145
	v_pk_fma_f32 v[32:33], v[32:33], 0.5, v[40:41] op_sel_hi:[1,0,1]
	v_pk_fma_f32 v[30:31], v[30:31], 0.5, v[38:39] op_sel_hi:[1,0,1]
	v_pk_fma_f32 v[38:39], v[28:29], 0.5, v[44:45] op_sel_hi:[1,0,1]
	v_pk_fma_f32 v[28:29], v[26:27], 0.5, v[42:43] op_sel_hi:[1,0,1]
	v_mul_f32_e32 v26, v31, v31
	v_mul_f32_e32 v27, v33, v33
	v_fmac_f32_e32 v26, v30, v30
	v_fmac_f32_e32 v27, v32, v32
	v_add_f32_e32 v26, v26, v27
	v_mul_f32_e32 v27, v29, v29
	v_fmac_f32_e32 v27, v28, v28
	v_add_f32_e32 v26, v27, v26
	v_mul_f32_e32 v27, v39, v39
	v_fmac_f32_e32 v27, v38, v38
	v_add_f32_e32 v44, v27, v26
	v_cvt_pk_bf16_f32 v26, v30, v31
	v_cvt_pk_bf16_f32 v27, v32, v33
	v_lshlrev_b32_e32 v30, 16, v138
	v_and_b32_e32 v31, 0xffff0000, v138
	v_lshlrev_b32_e32 v32, 16, v139
	v_and_b32_e32 v33, 0xffff0000, v139
	v_lshlrev_b32_e32 v40, 16, v140
	v_and_b32_e32 v41, 0xffff0000, v140
	v_pk_fma_f32 v[24:25], v[24:25], 0.5, v[32:33] op_sel_hi:[1,0,1]
	v_pk_fma_f32 v[22:23], v[22:23], 0.5, v[30:31] op_sel_hi:[1,0,1]
	v_pk_fma_f32 v[32:33], v[18:19], 0.5, v[40:41] op_sel_hi:[1,0,1]
	v_mul_f32_e32 v18, v23, v23
	v_mul_f32_e32 v19, v25, v25
	v_fmac_f32_e32 v18, v22, v22
	v_fmac_f32_e32 v19, v24, v24
	v_lshlrev_b32_e32 v42, 16, v141
	v_and_b32_e32 v43, 0xffff0000, v141
	v_add_f32_e32 v18, v18, v19
	v_mul_f32_e32 v19, v33, v33
	v_pk_fma_f32 v[30:31], v[20:21], 0.5, v[42:43] op_sel_hi:[1,0,1]
	v_fmac_f32_e32 v19, v32, v32
	v_add_f32_e32 v18, v19, v18
	v_mul_f32_e32 v19, v31, v31
	v_fmac_f32_e32 v19, v30, v30
	v_add_f32_e32 v18, v19, v18
	v_add_f32_e32 v18, v44, v18
	v_mov_b32_e32 v19, v18
	s_nop 1
	v_permlane16_swap_b32_e32 v18, v19
	s_mov_b64 s[40:41], 0x50000
	s_waitcnt lgkmcnt(1)
	v_lshl_add_u64 v[34:35], v[208:209], 0, s[40:41]
	s_mov_b64 s[40:41], 0x50100
	v_lshl_add_u64 v[36:37], v[208:209], 0, s[40:41]
	s_waitcnt lgkmcnt(0)
	v_add_f32_e32 v18, v18, v19
	v_mov_b32_e32 v19, v18
	s_nop 1
	v_permlane32_swap_b32_e32 v18, v19
	v_cvt_pk_bf16_f32 v28, v28, v29
	v_cvt_pk_bf16_f32 v29, v38, v39
	v_cvt_pk_bf16_f32 v20, v22, v23
	v_cvt_pk_bf16_f32 v21, v24, v25
	v_cvt_pk_bf16_f32 v22, v32, v33
	v_cvt_pk_bf16_f32 v23, v30, v31
	global_store_dwordx4 v[34:35], v[26:29], off
	global_store_dwordx4 v[36:37], v[20:23], off
	s_and_saveexec_b64 s[40:41], s[4:5]
	s_cbranch_execz .LBB0_695
	v_add_u32_e32 v20, 0xa0, v206
	v_ashrrev_i32_e32 v21, 31, v20
	s_waitcnt lgkmcnt(0)
	v_add_f32_e32 v22, v18, v19
	v_lshlrev_b64 v[18:19], 6, v[20:21]
	v_lshl_add_u64 v[18:19], s[22:23], 0, v[18:19]
	v_lshl_add_u64 v[18:19], s[38:39], 2, v[18:19]
	s_lshl_b32 s18, s55, 2
	v_lshl_add_u64 v[18:19], v[18:19], 0, s[18:19]
	global_store_dword v[18:19], v22, off
.LBB0_695:
	s_or_b64 exec, exec, s[40:41]
	v_lshlrev_b32_e32 v22, 16, v126
	v_and_b32_e32 v23, 0xffff0000, v126
	v_lshlrev_b32_e32 v24, 16, v127
	v_and_b32_e32 v25, 0xffff0000, v127
	v_lshlrev_b32_e32 v26, 16, v128
	v_and_b32_e32 v27, 0xffff0000, v128
	v_lshlrev_b32_e32 v28, 16, v129
	v_and_b32_e32 v29, 0xffff0000, v129
	v_pk_fma_f32 v[16:17], v[16:17], 0.5, v[24:25] op_sel_hi:[1,0,1]
	v_pk_fma_f32 v[14:15], v[14:15], 0.5, v[22:23] op_sel_hi:[1,0,1]
	v_pk_fma_f32 v[22:23], v[12:13], 0.5, v[28:29] op_sel_hi:[1,0,1]
	v_pk_fma_f32 v[12:13], v[10:11], 0.5, v[26:27] op_sel_hi:[1,0,1]
	v_mul_f32_e32 v10, v15, v15
	v_mul_f32_e32 v11, v17, v17
	v_fmac_f32_e32 v10, v14, v14
	v_fmac_f32_e32 v11, v16, v16
	v_add_f32_e32 v10, v10, v11
	v_mul_f32_e32 v11, v13, v13
	v_fmac_f32_e32 v11, v12, v12
	v_add_f32_e32 v10, v11, v10
	v_mul_f32_e32 v11, v23, v23
	v_fmac_f32_e32 v11, v22, v22
	v_add_f32_e32 v28, v11, v10
	v_cvt_pk_bf16_f32 v10, v14, v15
	v_cvt_pk_bf16_f32 v11, v16, v17
	v_lshlrev_b32_e32 v14, 16, v118
	v_and_b32_e32 v15, 0xffff0000, v118
	v_lshlrev_b32_e32 v16, 16, v119
	v_and_b32_e32 v17, 0xffff0000, v119
	v_lshlrev_b32_e32 v24, 16, v120
	v_and_b32_e32 v25, 0xffff0000, v120
	v_pk_fma_f32 v[8:9], v[8:9], 0.5, v[16:17] op_sel_hi:[1,0,1]
	v_pk_fma_f32 v[6:7], v[6:7], 0.5, v[14:15] op_sel_hi:[1,0,1]
	v_pk_fma_f32 v[16:17], v[2:3], 0.5, v[24:25] op_sel_hi:[1,0,1]
	v_mul_f32_e32 v2, v7, v7
	v_mul_f32_e32 v3, v9, v9
	v_fmac_f32_e32 v2, v6, v6
	v_fmac_f32_e32 v3, v8, v8
	v_lshlrev_b32_e32 v26, 16, v121
	v_and_b32_e32 v27, 0xffff0000, v121
	v_add_f32_e32 v2, v2, v3
	v_mul_f32_e32 v3, v17, v17
	v_pk_fma_f32 v[14:15], v[4:5], 0.5, v[26:27] op_sel_hi:[1,0,1]
	v_fmac_f32_e32 v3, v16, v16
	v_add_f32_e32 v2, v3, v2
	v_mul_f32_e32 v3, v15, v15
	v_fmac_f32_e32 v3, v14, v14
	v_add_f32_e32 v2, v3, v2
	v_add_f32_e32 v2, v28, v2
	v_mov_b32_e32 v3, v2
	s_nop 1
	v_permlane16_swap_b32_e32 v2, v3
	s_mov_b64 s[40:41], 0x58000
	s_waitcnt lgkmcnt(1)
	v_lshl_add_u64 v[18:19], v[208:209], 0, s[40:41]
	s_mov_b64 s[40:41], 0x58100
	v_lshl_add_u64 v[20:21], v[208:209], 0, s[40:41]
	s_waitcnt lgkmcnt(0)
	v_add_f32_e32 v2, v2, v3
	v_mov_b32_e32 v3, v2
	s_nop 1
	v_permlane32_swap_b32_e32 v2, v3
	v_cvt_pk_bf16_f32 v12, v12, v13
	v_cvt_pk_bf16_f32 v13, v22, v23
	v_cvt_pk_bf16_f32 v4, v6, v7
	v_cvt_pk_bf16_f32 v5, v8, v9
	v_cvt_pk_bf16_f32 v6, v16, v17
	v_cvt_pk_bf16_f32 v7, v14, v15
	global_store_dwordx4 v[18:19], v[10:13], off
	global_store_dwordx4 v[20:21], v[4:7], off
	s_and_saveexec_b64 s[40:41], s[4:5]
	s_cbranch_execz .LBB0_697
	v_add_u32_e32 v4, 0xb0, v206
	v_ashrrev_i32_e32 v5, 31, v4
	s_waitcnt lgkmcnt(0)
	v_add_f32_e32 v6, v2, v3
	v_lshlrev_b64 v[2:3], 6, v[4:5]
	v_lshl_add_u64 v[2:3], s[22:23], 0, v[2:3]
	v_lshl_add_u64 v[2:3], s[38:39], 2, v[2:3]
	s_lshl_b32 s18, s55, 2
	v_lshl_add_u64 v[2:3], v[2:3], 0, s[18:19]
	global_store_dword v[2:3], v6, off

;     __device__ __forceinline__ void operator()(const Acc& acc, const Unit& u, int wr, int wc, int fr, int fq) const {
;     ...
;             f32x4 gq[2][2];
;             { const float* gn = pn < 16 ? qn : kn;
;               _Pragma("unroll") for (int bj = 0; bj < 2; ++bj) { gq[bj][0] = *(const f32x4*)(gn + bj * 32 + 8 * fq); gq[bj][1] = *(const f32x4*)(gn + bj * 32 + 8 * fq + 4); } }
;             const bool isq = pn < 16;
;             EPI_IN_ROWS({
;                 float s = 0.f;
;                 _Pragma("unroll") for (int bj = 0; bj < 2; ++bj)
;                     _Pragma("unroll") for (int n = 0; n < 2; ++n) s += (v[bj][n][0] * v[bj][n][0] + v[bj][n][1] * v[bj][n][1]) + (v[bj][n][2] * v[bj][n][2] + v[bj][n][3] * v[bj][n][3]);
;                 s += __shfl_xor(s, 16); s += __shfl_xor(s, 32);
;                 const float hr = __builtin_amdgcn_rsqf(s * (1.0f / 64.0f) + EPS);
;                 const float sc = isq ? (0.125f * LOG2E) * hr : hr;
.LBB0_833:
	s_andn2_b64 vcc, exec, s[4:5]
	s_cbranch_vccnz .LBB0_923
	s_cmp_eq_u32 s10, 16
	s_cselect_b64 s[86:87], -1, 0
	s_cmp_lg_u32 s10, 16
	s_cselect_b64 s[4:5], -1, 0
	s_and_b64 s[6:7], s[4:5], exec
	s_cselect_b32 s7, s63, s65
	s_cselect_b32 s6, s62, s64
	v_lshlrev_b32_e32 v180, 2, v164
	global_load_dwordx4 v[138:141], v180, s[6:7] offset:16
	global_load_dwordx4 v[142:145], v180, s[6:7]
	global_load_dwordx4 v[130:133], v180, s[6:7] offset:144
	global_load_dwordx4 v[134:137], v180, s[6:7] offset:128
	v_and_b32_e32 v147, 64, v214
	v_add_u32_e32 v217, s25, v209
	v_xor_b32_e32 v146, 16, v214
	v_add_u32_e32 v147, 64, v147
	ds_read_b32 v162, v217
	v_cmp_lt_i32_e32 vcc, v146, v147
	s_lshl_b32 s55, s30, 8
	v_readlane_b32 s6, v252, 41
	v_cndmask_b32_e32 v146, v214, v146, vcc
	v_lshlrev_b32_e32 v216, 2, v146
	v_xor_b32_e32 v146, 32, v214
	v_cmp_lt_i32_e32 vcc, v146, v147
	s_waitcnt lgkmcnt(0)
	v_pk_mul_f32 v[148:149], v[126:127], v[162:163] op_sel_hi:[1,0]
	v_pk_mul_f32 v[150:151], v[124:125], v[162:163] op_sel_hi:[1,0]
	v_cndmask_b32_e32 v181, v214, v146, vcc
	v_pk_mul_f32 v[146:147], v[128:129], v[162:163] op_sel_hi:[1,0]
	v_pk_mul_f32 v[152:153], v[122:123], v[162:163] op_sel_hi:[1,0]
	v_pk_mul_f32 v[186:187], v[120:121], v[162:163] op_sel_hi:[1,0]
	v_pk_mul_f32 v[188:189], v[118:119], v[162:163] op_sel_hi:[1,0]
	v_pk_mul_f32 v[182:183], v[116:117], v[162:163] op_sel_hi:[1,0]
	v_pk_mul_f32 v[184:185], v[114:115], v[162:163] op_sel_hi:[1,0]
	v_mul_f32_e32 v162, v149, v149
	v_mul_f32_e32 v190, v147, v147
	v_fmac_f32_e32 v162, v148, v148
	v_fmac_f32_e32 v190, v146, v146
	v_add_f32_e32 v162, v162, v190
	v_mul_f32_e32 v190, v153, v153
	v_mul_f32_e32 v191, v151, v151
	v_fmac_f32_e32 v190, v152, v152
	v_fmac_f32_e32 v191, v150, v150
	v_add_f32_e32 v190, v190, v191
	v_add_f32_e32 v162, v162, v190
	v_mul_f32_e32 v190, v189, v189
	v_mul_f32_e32 v191, v187, v187
	v_fmac_f32_e32 v190, v188, v188
	v_fmac_f32_e32 v191, v186, v186
	v_add_f32_e32 v190, v190, v191
	v_add_f32_e32 v162, v190, v162
	v_mul_f32_e32 v190, v185, v185
	v_mul_f32_e32 v191, v183, v183
	v_fmac_f32_e32 v190, v184, v184
	v_fmac_f32_e32 v191, v182, v182
	v_add_f32_e32 v190, v190, v191
	v_add_f32_e32 v162, v190, v162
	v_mov_b32_e32 v190, v162
	s_nop 1
	v_permlane16_swap_b32_e32 v162, v190
	v_lshlrev_b32_e32 v218, 2, v181
	s_add_i32 s77, s55, s6
	v_or_b32_e32 v194, s77, v165
	v_ashrrev_i32_e32 v195, 31, v194
	s_waitcnt lgkmcnt(0)
	v_add_f32_e32 v162, v162, v190
	v_mov_b32_e32 v181, v162
	s_nop 1
	v_permlane32_swap_b32_e32 v162, v181
	s_mov_b64 s[6:7], -1
	s_and_b64 vcc, exec, s[86:87]
	v_lshlrev_b64 v[190:191], 10, v[194:195]
	s_cbranch_vccz .LBB0_836
	v_lshl_add_u64 v[192:193], s[90:91], 0, v[190:191]
	s_mov_b64 s[6:7], 0

;     __device__ __forceinline__ void operator()(const Acc& acc, const Unit& u, int wr, int wc, int fr, int fq) const {
;     ...
;             EPI_IN_ROWS({
;                 float s = 0.f;
;                 _Pragma("unroll") for (int bj = 0; bj < 2; ++bj)
;                     _Pragma("unroll") for (int n = 0; n < 2; ++n) s += (v[bj][n][0] * v[bj][n][0] + v[bj][n][1] * v[bj][n][1]) + (v[bj][n][2] * v[bj][n][2] + v[bj][n][3] * v[bj][n][3]);
;                 s += __shfl_xor(s, 16); s += __shfl_xor(s, 32);
;                 const float hr = __builtin_amdgcn_rsqf(s * (1.0f / 64.0f) + EPS);
;                 const float sc = isq ? (0.125f * LOG2E) * hr : hr;
.LBB0_842:
	ds_read_b32 v184, v217 offset:64
	v_or_b32_e32 v192, s77, v206
	v_ashrrev_i32_e32 v193, 31, v192
	s_mov_b64 s[72:73], -1
	s_and_b64 vcc, exec, s[86:87]
	s_waitcnt lgkmcnt(0)
	v_pk_mul_f32 v[146:147], v[112:113], v[184:185] op_sel_hi:[1,0]
	v_pk_mul_f32 v[148:149], v[110:111], v[184:185] op_sel_hi:[1,0]
	v_mul_f32_e32 v190, v147, v147
	v_mul_f32_e32 v181, v149, v149
	v_pk_mul_f32 v[150:151], v[108:109], v[184:185] op_sel_hi:[1,0]
	v_pk_mul_f32 v[152:153], v[106:107], v[184:185] op_sel_hi:[1,0]
	v_fmac_f32_e32 v181, v148, v148
	v_fmac_f32_e32 v190, v146, v146
	v_add_f32_e32 v181, v181, v190
	v_mul_f32_e32 v190, v153, v153
	v_mul_f32_e32 v191, v151, v151
	v_fmac_f32_e32 v190, v152, v152
	v_fmac_f32_e32 v191, v150, v150
	v_pk_mul_f32 v[186:187], v[104:105], v[184:185] op_sel_hi:[1,0]
	v_pk_mul_f32 v[188:189], v[102:103], v[184:185] op_sel_hi:[1,0]
	v_add_f32_e32 v190, v190, v191
	v_add_f32_e32 v181, v181, v190
	v_mul_f32_e32 v190, v189, v189
	v_mul_f32_e32 v191, v187, v187
	v_fmac_f32_e32 v190, v188, v188
	v_fmac_f32_e32 v191, v186, v186
	v_pk_mul_f32 v[182:183], v[100:101], v[184:185] op_sel_hi:[1,0]
	v_pk_mul_f32 v[184:185], v[98:99], v[184:185] op_sel_hi:[1,0]
	v_add_f32_e32 v190, v190, v191
	v_add_f32_e32 v181, v190, v181
	v_mul_f32_e32 v190, v185, v185
	v_mul_f32_e32 v191, v183, v183
	v_fmac_f32_e32 v190, v184, v184
	v_fmac_f32_e32 v191, v182, v182
	v_add_f32_e32 v190, v190, v191
	v_add_f32_e32 v181, v190, v181
	v_mov_b32_e32 v190, v181
	s_nop 1
	v_permlane16_swap_b32_e32 v181, v190
	s_waitcnt lgkmcnt(0)
	v_add_f32_e32 v181, v181, v190
	v_mov_b32_e32 v219, v181
	s_nop 1
	v_permlane32_swap_b32_e32 v181, v219
	v_lshlrev_b64 v[190:191], 10, v[192:193]
	s_cbranch_vccz .LBB0_844
	v_lshl_add_u64 v[194:195], s[90:91], 0, v[190:191]
	s_mov_b64 s[72:73], 0

;     __device__ __forceinline__ void operator()(const Acc& acc, const Unit& u, int wr, int wc, int fr, int fq) const {
;     ...
;             EPI_IN_ROWS({
;                 float s = 0.f;
;                 _Pragma("unroll") for (int bj = 0; bj < 2; ++bj)
;                     _Pragma("unroll") for (int n = 0; n < 2; ++n) s += (v[bj][n][0] * v[bj][n][0] + v[bj][n][1] * v[bj][n][1]) + (v[bj][n][2] * v[bj][n][2] + v[bj][n][3] * v[bj][n][3]);
;                 s += __shfl_xor(s, 16); s += __shfl_xor(s, 32);
;                 const float hr = __builtin_amdgcn_rsqf(s * (1.0f / 64.0f) + EPS);
;                 const float sc = isq ? (0.125f * LOG2E) * hr : hr;
.LBB0_850:
	ds_read_b32 v184, v217 offset:128
	v_or_b32_e32 v192, s77, v207
	v_ashrrev_i32_e32 v193, 31, v192
	s_mov_b64 s[72:73], -1
	s_and_b64 vcc, exec, s[86:87]
	s_waitcnt lgkmcnt(0)
	v_pk_mul_f32 v[146:147], v[96:97], v[184:185] op_sel_hi:[1,0]
	v_pk_mul_f32 v[148:149], v[94:95], v[184:185] op_sel_hi:[1,0]
	v_mul_f32_e32 v190, v147, v147
	v_mul_f32_e32 v181, v149, v149
	v_pk_mul_f32 v[150:151], v[92:93], v[184:185] op_sel_hi:[1,0]
	v_pk_mul_f32 v[152:153], v[90:91], v[184:185] op_sel_hi:[1,0]
	v_fmac_f32_e32 v181, v148, v148
	v_fmac_f32_e32 v190, v146, v146
	v_add_f32_e32 v181, v181, v190
	v_mul_f32_e32 v190, v153, v153
	v_mul_f32_e32 v191, v151, v151
	v_fmac_f32_e32 v190, v152, v152
	v_fmac_f32_e32 v191, v150, v150
	v_pk_mul_f32 v[186:187], v[88:89], v[184:185] op_sel_hi:[1,0]
	v_pk_mul_f32 v[188:189], v[86:87], v[184:185] op_sel_hi:[1,0]
	v_add_f32_e32 v190, v190, v191
	v_add_f32_e32 v181, v181, v190
	v_mul_f32_e32 v190, v189, v189
	v_mul_f32_e32 v191, v187, v187
	v_fmac_f32_e32 v190, v188, v188
	v_fmac_f32_e32 v191, v186, v186
	v_pk_mul_f32 v[182:183], v[84:85], v[184:185] op_sel_hi:[1,0]
	v_pk_mul_f32 v[184:185], v[82:83], v[184:185] op_sel_hi:[1,0]
	v_add_f32_e32 v190, v190, v191
	v_add_f32_e32 v181, v190, v181
	v_mul_f32_e32 v190, v185, v185
	v_mul_f32_e32 v191, v183, v183
	v_fmac_f32_e32 v190, v184, v184
	v_fmac_f32_e32 v191, v182, v182
	v_add_f32_e32 v190, v190, v191
	v_add_f32_e32 v181, v190, v181
	v_mov_b32_e32 v190, v181
	s_nop 1
	v_permlane16_swap_b32_e32 v181, v190
	s_waitcnt lgkmcnt(0)
	v_add_f32_e32 v181, v181, v190
	v_mov_b32_e32 v219, v181
	s_nop 1
	v_permlane32_swap_b32_e32 v181, v219
	v_lshlrev_b64 v[190:191], 10, v[192:193]
	s_cbranch_vccz .LBB0_852
	v_lshl_add_u64 v[194:195], s[90:91], 0, v[190:191]
	s_mov_b64 s[72:73], 0

;     __device__ __forceinline__ void operator()(const Acc& acc, const Unit& u, int wr, int wc, int fr, int fq) const {
;     ...
;             EPI_IN_ROWS({
;                 float s = 0.f;
;                 _Pragma("unroll") for (int bj = 0; bj < 2; ++bj)
;                     _Pragma("unroll") for (int n = 0; n < 2; ++n) s += (v[bj][n][0] * v[bj][n][0] + v[bj][n][1] * v[bj][n][1]) + (v[bj][n][2] * v[bj][n][2] + v[bj][n][3] * v[bj][n][3]);
;                 s += __shfl_xor(s, 16); s += __shfl_xor(s, 32);
;                 const float hr = __builtin_amdgcn_rsqf(s * (1.0f / 64.0f) + EPS);
;                 const float sc = isq ? (0.125f * LOG2E) * hr : hr;
.LBB0_858:
	ds_read_b32 v184, v217 offset:192
	v_or_b32_e32 v192, s77, v208
	v_ashrrev_i32_e32 v193, 31, v192
	s_mov_b64 s[72:73], -1
	s_and_b64 vcc, exec, s[86:87]
	s_waitcnt lgkmcnt(0)
	v_pk_mul_f32 v[146:147], v[80:81], v[184:185] op_sel_hi:[1,0]
	v_pk_mul_f32 v[148:149], v[78:79], v[184:185] op_sel_hi:[1,0]
	v_mul_f32_e32 v190, v147, v147
	v_mul_f32_e32 v181, v149, v149
	v_pk_mul_f32 v[150:151], v[76:77], v[184:185] op_sel_hi:[1,0]
	v_pk_mul_f32 v[152:153], v[74:75], v[184:185] op_sel_hi:[1,0]
	v_fmac_f32_e32 v181, v148, v148
	v_fmac_f32_e32 v190, v146, v146
	v_add_f32_e32 v181, v181, v190
	v_mul_f32_e32 v190, v153, v153
	v_mul_f32_e32 v191, v151, v151
	v_fmac_f32_e32 v190, v152, v152
	v_fmac_f32_e32 v191, v150, v150
	v_pk_mul_f32 v[186:187], v[72:73], v[184:185] op_sel_hi:[1,0]
	v_pk_mul_f32 v[188:189], v[70:71], v[184:185] op_sel_hi:[1,0]
	v_add_f32_e32 v190, v190, v191
	v_add_f32_e32 v181, v181, v190
	v_mul_f32_e32 v190, v189, v189
	v_mul_f32_e32 v191, v187, v187
	v_fmac_f32_e32 v190, v188, v188
	v_fmac_f32_e32 v191, v186, v186
	v_pk_mul_f32 v[182:183], v[68:69], v[184:185] op_sel_hi:[1,0]
	v_pk_mul_f32 v[184:185], v[66:67], v[184:185] op_sel_hi:[1,0]
	v_add_f32_e32 v190, v190, v191
	v_add_f32_e32 v181, v190, v181
	v_mul_f32_e32 v190, v185, v185
	v_mul_f32_e32 v191, v183, v183
	v_fmac_f32_e32 v190, v184, v184
	v_fmac_f32_e32 v191, v182, v182
	v_add_f32_e32 v190, v190, v191
	v_add_f32_e32 v181, v190, v181
	v_mov_b32_e32 v190, v181
	s_nop 1
	v_permlane16_swap_b32_e32 v181, v190
	s_waitcnt lgkmcnt(0)
	v_add_f32_e32 v181, v181, v190
	v_mov_b32_e32 v219, v181
	s_nop 1
	v_permlane32_swap_b32_e32 v181, v219
	v_lshlrev_b64 v[190:191], 10, v[192:193]
	s_cbranch_vccz .LBB0_860
	v_lshl_add_u64 v[194:195], s[90:91], 0, v[190:191]
	s_mov_b64 s[72:73], 0

;     __device__ __forceinline__ void operator()(const Acc& acc, const Unit& u, int wr, int wc, int fr, int fq) const {
;     ...
;             EPI_IN_ROWS({
;                 float s = 0.f;
;                 _Pragma("unroll") for (int bj = 0; bj < 2; ++bj)
;                     _Pragma("unroll") for (int n = 0; n < 2; ++n) s += (v[bj][n][0] * v[bj][n][0] + v[bj][n][1] * v[bj][n][1]) + (v[bj][n][2] * v[bj][n][2] + v[bj][n][3] * v[bj][n][3]);
;                 s += __shfl_xor(s, 16); s += __shfl_xor(s, 32);
;                 const float hr = __builtin_amdgcn_rsqf(s * (1.0f / 64.0f) + EPS);
;                 const float sc = isq ? (0.125f * LOG2E) * hr : hr;
.LBB0_866:
	ds_read_b32 v184, v217 offset:512
	v_readlane_b32 s6, v252, 42
	s_add_i32 s55, s55, s6
	v_or_b32_e32 v194, s55, v165
	v_ashrrev_i32_e32 v195, 31, v194
	s_waitcnt lgkmcnt(0)
	v_pk_mul_f32 v[146:147], v[64:65], v[184:185] op_sel_hi:[1,0]
	v_pk_mul_f32 v[148:149], v[62:63], v[184:185] op_sel_hi:[1,0]
	v_mul_f32_e32 v190, v147, v147
	v_mul_f32_e32 v181, v149, v149
	v_pk_mul_f32 v[150:151], v[60:61], v[184:185] op_sel_hi:[1,0]
	v_pk_mul_f32 v[152:153], v[58:59], v[184:185] op_sel_hi:[1,0]
	v_fmac_f32_e32 v181, v148, v148
	v_fmac_f32_e32 v190, v146, v146
	v_add_f32_e32 v181, v181, v190
	v_mul_f32_e32 v190, v153, v153
	v_mul_f32_e32 v191, v151, v151
	v_fmac_f32_e32 v190, v152, v152
	v_fmac_f32_e32 v191, v150, v150
	v_pk_mul_f32 v[186:187], v[56:57], v[184:185] op_sel_hi:[1,0]
	v_pk_mul_f32 v[188:189], v[54:55], v[184:185] op_sel_hi:[1,0]
	v_add_f32_e32 v190, v190, v191
	v_add_f32_e32 v181, v181, v190
	v_mul_f32_e32 v190, v189, v189
	v_mul_f32_e32 v191, v187, v187
	v_fmac_f32_e32 v190, v188, v188
	v_fmac_f32_e32 v191, v186, v186
	v_pk_mul_f32 v[182:183], v[52:53], v[184:185] op_sel_hi:[1,0]
	v_pk_mul_f32 v[184:185], v[50:51], v[184:185] op_sel_hi:[1,0]
	v_add_f32_e32 v190, v190, v191
	v_add_f32_e32 v181, v190, v181
	v_mul_f32_e32 v190, v185, v185
	v_mul_f32_e32 v191, v183, v183
	v_fmac_f32_e32 v190, v184, v184
	v_fmac_f32_e32 v191, v182, v182
	v_add_f32_e32 v190, v190, v191
	v_add_f32_e32 v181, v190, v181
	v_mov_b32_e32 v190, v181
	s_nop 1
	v_permlane16_swap_b32_e32 v181, v190
	s_mov_b64 s[6:7], -1
	s_and_b64 vcc, exec, s[86:87]
	s_waitcnt lgkmcnt(0)
	v_add_f32_e32 v181, v181, v190
	v_mov_b32_e32 v219, v181
	s_nop 1
	v_permlane32_swap_b32_e32 v181, v219
	s_cbranch_vccz .LBB0_868
	v_lshlrev_b64 v[190:191], 10, v[194:195]
	v_lshl_add_u64 v[192:193], s[90:91], 0, v[190:191]
	s_mov_b64 s[6:7], 0

;     __device__ __forceinline__ void operator()(const Acc& acc, const Unit& u, int wr, int wc, int fr, int fq) const {
;     ...
;             EPI_IN_ROWS({
;                 float s = 0.f;
;                 _Pragma("unroll") for (int bj = 0; bj < 2; ++bj)
;                     _Pragma("unroll") for (int n = 0; n < 2; ++n) s += (v[bj][n][0] * v[bj][n][0] + v[bj][n][1] * v[bj][n][1]) + (v[bj][n][2] * v[bj][n][2] + v[bj][n][3] * v[bj][n][3]);
;                 s += __shfl_xor(s, 16); s += __shfl_xor(s, 32);
;                 const float hr = __builtin_amdgcn_rsqf(s * (1.0f / 64.0f) + EPS);
;                 const float sc = isq ? (0.125f * LOG2E) * hr : hr;
.LBB0_880:
	s_or_b64 exec, exec, s[72:73]
	ds_read_b32 v184, v217 offset:576
	v_or_b32_e32 v194, s55, v206
	v_ashrrev_i32_e32 v195, 31, v194
	s_mov_b64 s[72:73], -1
	s_and_b64 vcc, exec, s[86:87]
	s_waitcnt lgkmcnt(0)
	v_pk_mul_f32 v[146:147], v[48:49], v[184:185] op_sel_hi:[1,0]
	v_pk_mul_f32 v[148:149], v[46:47], v[184:185] op_sel_hi:[1,0]
	v_mul_f32_e32 v190, v147, v147
	v_mul_f32_e32 v181, v149, v149
	v_pk_mul_f32 v[150:151], v[44:45], v[184:185] op_sel_hi:[1,0]
	v_pk_mul_f32 v[152:153], v[42:43], v[184:185] op_sel_hi:[1,0]
	v_fmac_f32_e32 v181, v148, v148
	v_fmac_f32_e32 v190, v146, v146
	v_add_f32_e32 v181, v181, v190
	v_mul_f32_e32 v190, v153, v153
	v_mul_f32_e32 v191, v151, v151
	v_fmac_f32_e32 v190, v152, v152
	v_fmac_f32_e32 v191, v150, v150
	v_pk_mul_f32 v[186:187], v[40:41], v[184:185] op_sel_hi:[1,0]
	v_pk_mul_f32 v[188:189], v[38:39], v[184:185] op_sel_hi:[1,0]
	v_add_f32_e32 v190, v190, v191
	v_add_f32_e32 v181, v181, v190
	v_mul_f32_e32 v190, v189, v189
	v_mul_f32_e32 v191, v187, v187
	v_fmac_f32_e32 v190, v188, v188
	v_fmac_f32_e32 v191, v186, v186
	v_pk_mul_f32 v[182:183], v[36:37], v[184:185] op_sel_hi:[1,0]
	v_pk_mul_f32 v[184:185], v[34:35], v[184:185] op_sel_hi:[1,0]
	v_add_f32_e32 v190, v190, v191
	v_add_f32_e32 v181, v190, v181
	v_mul_f32_e32 v190, v185, v185
	v_mul_f32_e32 v191, v183, v183
	v_fmac_f32_e32 v190, v184, v184
	v_fmac_f32_e32 v191, v182, v182
	v_add_f32_e32 v190, v190, v191
	v_add_f32_e32 v181, v190, v181
	v_mov_b32_e32 v190, v181
	s_nop 1
	v_permlane16_swap_b32_e32 v181, v190
	s_waitcnt lgkmcnt(0)
	v_add_f32_e32 v181, v181, v190
	v_mov_b32_e32 v219, v181
	s_nop 1
	v_permlane32_swap_b32_e32 v181, v219
	s_cbranch_vccnz .LBB0_883
	s_andn2_b64 vcc, exec, s[72:73]
	s_cbranch_vccz .LBB0_884

;     __device__ __forceinline__ void operator()(const Acc& acc, const Unit& u, int wr, int wc, int fr, int fq) const {
;     ...
;             EPI_IN_ROWS({
;                 float s = 0.f;
;                 _Pragma("unroll") for (int bj = 0; bj < 2; ++bj)
;                     _Pragma("unroll") for (int n = 0; n < 2; ++n) s += (v[bj][n][0] * v[bj][n][0] + v[bj][n][1] * v[bj][n][1]) + (v[bj][n][2] * v[bj][n][2] + v[bj][n][3] * v[bj][n][3]);
;                 s += __shfl_xor(s, 16); s += __shfl_xor(s, 32);
;                 const float hr = __builtin_amdgcn_rsqf(s * (1.0f / 64.0f) + EPS);
;                 const float sc = isq ? (0.125f * LOG2E) * hr : hr;
.LBB0_894:
	s_or_b64 exec, exec, s[72:73]
	ds_read_b32 v184, v217 offset:640
	v_or_b32_e32 v194, s55, v207
	v_ashrrev_i32_e32 v195, 31, v194
	s_mov_b64 s[72:73], -1
	s_and_b64 vcc, exec, s[86:87]
	s_waitcnt lgkmcnt(0)
	v_pk_mul_f32 v[146:147], v[32:33], v[184:185] op_sel_hi:[1,0]
	v_pk_mul_f32 v[148:149], v[30:31], v[184:185] op_sel_hi:[1,0]
	v_mul_f32_e32 v190, v147, v147
	v_mul_f32_e32 v181, v149, v149
	v_pk_mul_f32 v[150:151], v[28:29], v[184:185] op_sel_hi:[1,0]
	v_pk_mul_f32 v[152:153], v[26:27], v[184:185] op_sel_hi:[1,0]
	v_fmac_f32_e32 v181, v148, v148
	v_fmac_f32_e32 v190, v146, v146
	v_add_f32_e32 v181, v181, v190
	v_mul_f32_e32 v190, v153, v153
	v_mul_f32_e32 v191, v151, v151
	v_fmac_f32_e32 v190, v152, v152
	v_fmac_f32_e32 v191, v150, v150
	v_pk_mul_f32 v[186:187], v[24:25], v[184:185] op_sel_hi:[1,0]
	v_pk_mul_f32 v[188:189], v[22:23], v[184:185] op_sel_hi:[1,0]
	v_add_f32_e32 v190, v190, v191
	v_add_f32_e32 v181, v181, v190
	v_mul_f32_e32 v190, v189, v189
	v_mul_f32_e32 v191, v187, v187
	v_fmac_f32_e32 v190, v188, v188
	v_fmac_f32_e32 v191, v186, v186
	v_pk_mul_f32 v[182:183], v[20:21], v[184:185] op_sel_hi:[1,0]
	v_pk_mul_f32 v[184:185], v[18:19], v[184:185] op_sel_hi:[1,0]
	v_add_f32_e32 v190, v190, v191
	v_add_f32_e32 v181, v190, v181
	v_mul_f32_e32 v190, v185, v185
	v_mul_f32_e32 v191, v183, v183
	v_fmac_f32_e32 v190, v184, v184
	v_fmac_f32_e32 v191, v182, v182
	v_add_f32_e32 v190, v190, v191
	v_add_f32_e32 v181, v190, v181
	v_mov_b32_e32 v190, v181
	s_nop 1
	v_permlane16_swap_b32_e32 v181, v190
	s_waitcnt lgkmcnt(0)
	v_add_f32_e32 v181, v181, v190
	v_mov_b32_e32 v219, v181
	s_nop 1
	v_permlane32_swap_b32_e32 v181, v219
	s_cbranch_vccnz .LBB0_897
	s_andn2_b64 vcc, exec, s[72:73]
	s_cbranch_vccz .LBB0_898

;     __device__ __forceinline__ void operator()(const Acc& acc, const Unit& u, int wr, int wc, int fr, int fq) const {
;     ...
;             EPI_IN_ROWS({
;                 float s = 0.f;
;                 _Pragma("unroll") for (int bj = 0; bj < 2; ++bj)
;                     _Pragma("unroll") for (int n = 0; n < 2; ++n) s += (v[bj][n][0] * v[bj][n][0] + v[bj][n][1] * v[bj][n][1]) + (v[bj][n][2] * v[bj][n][2] + v[bj][n][3] * v[bj][n][3]);
;                 s += __shfl_xor(s, 16); s += __shfl_xor(s, 32);
;                 const float hr = __builtin_amdgcn_rsqf(s * (1.0f / 64.0f) + EPS);
;                 const float sc = isq ? (0.125f * LOG2E) * hr : hr;
.LBB0_908:
	s_or_b64 exec, exec, s[72:73]
	ds_read_b32 v148, v217 offset:704
	v_or_b32_e32 v194, s55, v208
	v_ashrrev_i32_e32 v195, 31, v194
	s_mov_b64 s[72:73], -1
	s_and_b64 vcc, exec, s[86:87]
	s_waitcnt lgkmcnt(0)
	v_pk_mul_f32 v[184:185], v[16:17], v[148:149] op_sel_hi:[1,0]
	v_pk_mul_f32 v[188:189], v[14:15], v[148:149] op_sel_hi:[1,0]
	v_mul_f32_e32 v190, v185, v185
	v_mul_f32_e32 v181, v189, v189
	v_pk_mul_f32 v[182:183], v[12:13], v[148:149] op_sel_hi:[1,0]
	v_pk_mul_f32 v[186:187], v[10:11], v[148:149] op_sel_hi:[1,0]
	v_fmac_f32_e32 v181, v188, v188
	v_fmac_f32_e32 v190, v184, v184
	v_add_f32_e32 v181, v181, v190
	v_mul_f32_e32 v190, v187, v187
	v_mul_f32_e32 v191, v183, v183
	v_fmac_f32_e32 v190, v186, v186
	v_fmac_f32_e32 v191, v182, v182
	v_pk_mul_f32 v[150:151], v[8:9], v[148:149] op_sel_hi:[1,0]
	v_pk_mul_f32 v[152:153], v[6:7], v[148:149] op_sel_hi:[1,0]
	v_add_f32_e32 v190, v190, v191
	v_add_f32_e32 v181, v181, v190
	v_mul_f32_e32 v190, v153, v153
	v_mul_f32_e32 v191, v151, v151
	v_fmac_f32_e32 v190, v152, v152
	v_fmac_f32_e32 v191, v150, v150
	v_pk_mul_f32 v[146:147], v[4:5], v[148:149] op_sel_hi:[1,0]
	v_pk_mul_f32 v[148:149], v[2:3], v[148:149] op_sel_hi:[1,0]
	v_add_f32_e32 v190, v190, v191
	v_add_f32_e32 v181, v190, v181
	v_mul_f32_e32 v190, v149, v149
	v_mul_f32_e32 v191, v147, v147
	v_fmac_f32_e32 v190, v148, v148
	v_fmac_f32_e32 v191, v146, v146
	v_add_f32_e32 v190, v190, v191
	v_add_f32_e32 v181, v190, v181
	v_mov_b32_e32 v190, v181
	s_nop 1
	v_permlane16_swap_b32_e32 v181, v190
	s_waitcnt lgkmcnt(0)
	v_add_f32_e32 v181, v181, v190
	v_mov_b32_e32 v216, v181
	s_nop 1
	v_permlane32_swap_b32_e32 v181, v216
	s_cbranch_vccnz .LBB0_911
	s_andn2_b64 vcc, exec, s[72:73]
	s_cbranch_vccz .LBB0_912

; __device__ __forceinline__ u32x4 pack8(const f32x4 a, const f32x4 b) { u32x4 w; w.x = cvtpk(a[0], a[1]); w.y = cvtpk(a[2], a[3]); w.z = cvtpk(b[0], b[1]); w.w = cvtpk(b[2], b[3]); return w; }
; __device__ __forceinline__ void unpack8(const u32x4 w, f32x4& a, f32x4& b) { a = (f32x4){bflo(w.x), bfhi(w.x), bflo(w.y), bfhi(w.y)}; b = (f32x4){bflo(w.z), bfhi(w.z), bflo(w.w), bfhi(w.w)}; }
;     __device__ __forceinline__ void operator()(const Acc& acc, const Unit& u, int wr, int wc, int fr, int fq) const {
;         const size_t off0 = (size_t)(u.pm * BM + wr * 64 + fr) * D + u.pn * BM + wc * 32 + 8 * fq;
;         u32x4 bw[2][4][2];
; #pragma unroll
;         for (int ai = 0; ai < 2; ++ai)
; #pragma unroll
;             for (int m = 0; m < 4; ++m)
; #pragma unroll
;                 for (int bj = 0; bj < 2; ++bj) bw[ai][m][bj] = *(const u32x4*)((const bf16_t*)base + off0 + (size_t)(ai * HALF + m * 16) * D + bj * HALF);
; #pragma unroll
;         for (int ai = 0; ai < 2; ++ai)
; #pragma unroll
;             for (int m = 0; m < 4; ++m) {
;                 const int row = u.pm * BM + ai * HALF + wr * 64 + m * 16 + fr; float s = 0.f;
; #pragma unroll
;                 for (int bj = 0; bj < 2; ++bj) {
;                     const size_t off = off0 + (size_t)(ai * HALF + m * 16) * D + bj * HALF;
;                     f32x4 b0, b1; unpack8(bw[ai][m][bj], b0, b1);
;                     const f32x4 v0 = b0 + acc[ai][bj][m][0] * scale, v1 = b1 + acc[ai][bj][m][1] * scale;
;                     s += (v0[0] * v0[0] + v0[1] * v0[1]) + (v0[2] * v0[2] + v0[3] * v0[3]) + (v1[0] * v1[0] + v1[1] * v1[1]) + (v1[2] * v1[2] + v1[3] * v1[3]);
;                     if (OUT_F32) { *(f32x4*)(outf + off) = v0; *(f32x4*)(outf + off + 4) = v1; }
;                     if (OUT_BF16) *(u32x4*)(outb + off) = pack8(v0, v1);
;                 }
;                 s += __shfl_xor(s, 16); s += __shfl_xor(s, 32);
;                 if (fq == 0) ssq[(size_t)row * 16 + u.pn * 4 + wc] = s;
.LBB0_1579:
	v_lshl_add_u32 v206, s8, 8, v209
	v_ashrrev_i32_e32 v207, 31, v206
	s_lshl_b32 s8, s14, 8
	v_lshlrev_b64 v[106:107], 10, v[206:207]
	s_ashr_i32 s9, s8, 31
	v_lshl_add_u64 v[106:107], v[106:107], 0, s[8:9]
	v_or_b32_e32 v106, v106, v194
	v_lshlrev_b64 v[226:227], 1, v[106:107]
	v_lshl_add_u64 v[106:107], s[88:89], 0, v[226:227]
	global_load_dwordx4 v[218:221], v[106:107], off
	global_load_dwordx4 v[222:225], v[106:107], off offset:256
	v_add_co_u32_e64 v114, s[8:9], s43, v106
	v_add_co_u32_e32 v108, vcc, s54, v106
	s_nop 0
	v_addc_co_u32_e64 v115, s[8:9], 0, v107, s[8:9]
	v_add_co_u32_e64 v116, s[8:9], s53, v106
	v_addc_co_u32_e32 v109, vcc, 0, v107, vcc
	s_nop 0
	v_addc_co_u32_e64 v117, s[8:9], 0, v107, s[8:9]
	global_load_dwordx4 v[174:177], v[114:115], off
	global_load_dwordx4 v[170:173], v[114:115], off offset:256
	global_load_dwordx4 v[166:169], v[116:117], off
	global_load_dwordx4 v[162:165], v[116:117], off offset:256
	v_add_co_u32_e32 v114, vcc, s59, v106
	global_load_dwordx4 v[182:185], v[108:109], off
	global_load_dwordx4 v[178:181], v[108:109], off offset:256
	v_addc_co_u32_e32 v115, vcc, 0, v107, vcc
	v_add_co_u32_e32 v108, vcc, s60, v106
	global_load_dwordx4 v[158:161], v[114:115], off
	global_load_dwordx4 v[154:157], v[114:115], off offset:256
	v_addc_co_u32_e32 v109, vcc, 0, v107, vcc
	v_add_co_u32_e32 v114, vcc, s61, v106
	global_load_dwordx4 v[150:153], v[108:109], off
	global_load_dwordx4 v[146:149], v[108:109], off offset:256
	v_addc_co_u32_e32 v115, vcc, 0, v107, vcc
	v_add_co_u32_e32 v106, vcc, s62, v106
	global_load_dwordx4 v[134:137], v[114:115], off
	global_load_dwordx4 v[130:133], v[114:115], off offset:256
	v_addc_co_u32_e32 v107, vcc, 0, v107, vcc
	global_load_dwordx4 v[114:117], v[106:107], off
	s_nop 0
	global_load_dwordx4 v[106:109], v[106:107], off offset:256
	v_and_b32_e32 v216, 64, v214
	v_xor_b32_e32 v215, 16, v214
	v_add_u32_e32 v216, 64, v216
	v_xor_b32_e32 v217, 32, v214
	v_cmp_lt_i32_e32 vcc, v215, v216
	s_lshl_b32 s8, s14, 2
	s_ashr_i32 s9, s8, 31
	v_cndmask_b32_e32 v215, v214, v215, vcc
	v_cmp_lt_i32_e32 vcc, v217, v216
	v_lshlrev_b32_e32 v216, 2, v215
	s_waitcnt vmcnt(0)
	v_lshlrev_b32_e32 v228, 16, v218
	v_and_b32_e32 v229, 0xffff0000, v218
	v_lshlrev_b32_e32 v218, 16, v219
	v_and_b32_e32 v219, 0xffff0000, v219
	v_cndmask_b32_e32 v217, v214, v217, vcc
	v_lshlrev_b32_e32 v230, 16, v220
	v_and_b32_e32 v231, 0xffff0000, v220
	v_lshlrev_b32_e32 v220, 16, v221
	v_and_b32_e32 v221, 0xffff0000, v221
	v_pk_add_f32 v[144:145], v[144:145], v[218:219]
	v_pk_add_f32 v[142:143], v[142:143], v[228:229]
	v_lshlrev_b32_e32 v215, 2, v217
	v_pk_add_f32 v[218:219], v[140:141], v[220:221]
	v_pk_add_f32 v[140:141], v[138:139], v[230:231]
	v_mul_f32_e32 v139, v143, v143
	v_mul_f32_e32 v217, v145, v145
	v_mul_f32_e32 v220, v141, v141
	v_fmac_f32_e32 v139, v142, v142
	v_fmac_f32_e32 v217, v144, v144
	v_mul_f32_e32 v221, v219, v219
	v_fmac_f32_e32 v220, v140, v140
	v_add_f32_e32 v139, v139, v217
	v_fmac_f32_e32 v221, v218, v218
	v_add_f32_e32 v139, v220, v139
	v_cvt_pk_bf16_f32 v138, v142, v143
	v_add_f32_e32 v217, v221, v139
	v_cvt_pk_bf16_f32 v139, v144, v145
	v_lshlrev_b32_e32 v142, 16, v222
	v_and_b32_e32 v143, 0xffff0000, v222
	v_lshlrev_b32_e32 v144, 16, v223
	v_and_b32_e32 v145, 0xffff0000, v223
	v_lshlrev_b32_e32 v220, 16, v224
	v_and_b32_e32 v221, 0xffff0000, v224
	v_pk_add_f32 v[128:129], v[128:129], v[144:145]
	v_pk_add_f32 v[126:127], v[126:127], v[142:143]
	v_pk_add_f32 v[144:145], v[122:123], v[220:221]
	v_mul_f32_e32 v122, v127, v127
	v_mul_f32_e32 v123, v129, v129
	v_fmac_f32_e32 v122, v126, v126
	v_fmac_f32_e32 v123, v128, v128
	v_lshlrev_b32_e32 v222, 16, v225
	v_and_b32_e32 v223, 0xffff0000, v225
	v_add_f32_e32 v122, v122, v123
	v_mul_f32_e32 v123, v145, v145
	v_pk_add_f32 v[142:143], v[124:125], v[222:223]
	v_fmac_f32_e32 v123, v144, v144
	v_add_f32_e32 v122, v123, v122
	v_mul_f32_e32 v123, v143, v143
	v_fmac_f32_e32 v123, v142, v142
	v_add_f32_e32 v122, v123, v122
	v_add_f32_e32 v124, v217, v122
	v_mov_b32_e32 v125, v124
	s_nop 1
	v_permlane16_swap_b32_e32 v124, v125
	v_cvt_pk_bf16_f32 v140, v140, v141
	v_cvt_pk_bf16_f32 v141, v218, v219
	v_lshl_add_u64 v[122:123], s[40:41], 0, v[226:227]
	v_cvt_pk_bf16_f32 v126, v126, v127
	s_waitcnt lgkmcnt(0)
	v_add_f32_e32 v124, v124, v125
	v_mov_b32_e32 v125, v124
	s_nop 1
	v_permlane32_swap_b32_e32 v124, v125
	v_cvt_pk_bf16_f32 v127, v128, v129
	v_cvt_pk_bf16_f32 v128, v144, v145
	v_cvt_pk_bf16_f32 v129, v142, v143
	global_store_dwordx4 v[122:123], v[138:141], off
	global_store_dwordx4 v[122:123], v[126:129], off offset:256
	s_and_saveexec_b64 s[30:31], s[4:5]
	s_cbranch_execz .LBB0_1581
	v_lshlrev_b64 v[126:127], 6, v[206:207]
	v_lshl_add_u64 v[126:127], s[10:11], 0, v[126:127]
	v_lshl_add_u64 v[126:127], s[8:9], 2, v[126:127]
	s_lshl_b32 s14, s44, 2
	v_lshl_add_u64 v[126:127], v[126:127], 0, s[14:15]
	s_waitcnt lgkmcnt(0)
	v_add_f32_e32 v124, v124, v125
	global_store_dword v[126:127], v124, off
; __device__ __forceinline__ u32x4 pack8(const f32x4 a, const f32x4 b) { u32x4 w; w.x = cvtpk(a[0], a[1]); w.y = cvtpk(a[2], a[3]); w.z = cvtpk(b[0], b[1]); w.w = cvtpk(b[2], b[3]); return w; }
; __device__ __forceinline__ void unpack8(const u32x4 w, f32x4& a, f32x4& b) { a = (f32x4){bflo(w.x), bfhi(w.x), bflo(w.y), bfhi(w.y)}; b = (f32x4){bflo(w.z), bfhi(w.z), bflo(w.w), bfhi(w.w)}; }
;     __device__ __forceinline__ void operator()(const Acc& acc, const Unit& u, int wr, int wc, int fr, int fq) const {
;     ...
;         for (int ai = 0; ai < 2; ++ai)
; #pragma unroll
;             for (int m = 0; m < 4; ++m) {
;                 const int row = u.pm * BM + ai * HALF + wr * 64 + m * 16 + fr; float s = 0.f;
; #pragma unroll
;                 for (int bj = 0; bj < 2; ++bj) {
;                     const size_t off = off0 + (size_t)(ai * HALF + m * 16) * D + bj * HALF;
;                     f32x4 b0, b1; unpack8(bw[ai][m][bj], b0, b1);
;                     const f32x4 v0 = b0 + acc[ai][bj][m][0] * scale, v1 = b1 + acc[ai][bj][m][1] * scale;
;                     s += (v0[0] * v0[0] + v0[1] * v0[1]) + (v0[2] * v0[2] + v0[3] * v0[3]) + (v1[0] * v1[0] + v1[1] * v1[1]) + (v1[2] * v1[2] + v1[3] * v1[3]);
;                     if (OUT_F32) { *(f32x4*)(outf + off) = v0; *(f32x4*)(outf + off + 4) = v1; }
;                     if (OUT_BF16) *(u32x4*)(outb + off) = pack8(v0, v1);
;                 }
;                 s += __shfl_xor(s, 16); s += __shfl_xor(s, 32);
;                 if (fq == 0) ssq[(size_t)row * 16 + u.pn * 4 + wc] = s;
.LBB0_1581:
	s_or_b64 exec, exec, s[30:31]
	v_lshlrev_b32_e32 v124, 16, v182
	s_waitcnt lgkmcnt(0)
	v_and_b32_e32 v125, 0xffff0000, v182
	v_lshlrev_b32_e32 v126, 16, v183
	v_and_b32_e32 v127, 0xffff0000, v183
	v_lshlrev_b32_e32 v128, 16, v184
	v_and_b32_e32 v129, 0xffff0000, v184
	v_lshlrev_b32_e32 v138, 16, v185
	v_and_b32_e32 v139, 0xffff0000, v185
	v_pk_add_f32 v[120:121], v[120:121], v[126:127]
	v_pk_add_f32 v[118:119], v[118:119], v[124:125]
	v_pk_add_f32 v[124:125], v[112:113], v[138:139]
	v_pk_add_f32 v[112:113], v[110:111], v[128:129]
	v_mul_f32_e32 v110, v119, v119
	v_mul_f32_e32 v111, v121, v121
	v_fmac_f32_e32 v110, v118, v118
	v_fmac_f32_e32 v111, v120, v120
	v_add_f32_e32 v110, v110, v111
	v_mul_f32_e32 v111, v113, v113
	v_fmac_f32_e32 v111, v112, v112
	v_add_f32_e32 v110, v111, v110
	v_mul_f32_e32 v111, v125, v125
	v_fmac_f32_e32 v111, v124, v124
	v_add_f32_e32 v128, v111, v110
	v_cvt_pk_bf16_f32 v110, v118, v119
	v_cvt_pk_bf16_f32 v111, v120, v121
	v_lshlrev_b32_e32 v118, 16, v178
	v_and_b32_e32 v119, 0xffff0000, v178
	v_lshlrev_b32_e32 v120, 16, v179
	v_and_b32_e32 v121, 0xffff0000, v179
	v_cvt_pk_bf16_f32 v112, v112, v113
	v_cvt_pk_bf16_f32 v113, v124, v125
	v_lshlrev_b32_e32 v124, 16, v180
	v_and_b32_e32 v125, 0xffff0000, v180
	v_pk_add_f32 v[104:105], v[104:105], v[120:121]
	v_pk_add_f32 v[102:103], v[102:103], v[118:119]
	v_pk_add_f32 v[120:121], v[98:99], v[124:125]
	v_mul_f32_e32 v98, v103, v103
	v_mul_f32_e32 v99, v105, v105
	v_fmac_f32_e32 v98, v102, v102
	v_fmac_f32_e32 v99, v104, v104
	v_lshlrev_b32_e32 v126, 16, v181
	v_and_b32_e32 v127, 0xffff0000, v181
	v_add_f32_e32 v98, v98, v99
	v_mul_f32_e32 v99, v121, v121
	v_pk_add_f32 v[118:119], v[100:101], v[126:127]
	v_fmac_f32_e32 v99, v120, v120
	v_add_f32_e32 v98, v99, v98
	v_mul_f32_e32 v99, v119, v119
	v_fmac_f32_e32 v99, v118, v118
	v_add_f32_e32 v98, v99, v98
	v_add_f32_e32 v98, v128, v98
	v_mov_b32_e32 v99, v98
	s_nop 1
	v_permlane16_swap_b32_e32 v98, v99
	v_add_co_u32_e32 v124, vcc, s54, v122
	v_cvt_pk_bf16_f32 v100, v102, v103
	s_nop 0
	v_addc_co_u32_e32 v125, vcc, 0, v123, vcc
	s_waitcnt lgkmcnt(0)
	v_add_f32_e32 v98, v98, v99
	v_mov_b32_e32 v99, v98
	s_nop 1
	v_permlane32_swap_b32_e32 v98, v99
	v_cvt_pk_bf16_f32 v101, v104, v105
	v_cvt_pk_bf16_f32 v102, v120, v121
	v_cvt_pk_bf16_f32 v103, v118, v119
	global_store_dwordx4 v[124:125], v[110:113], off
	global_store_dwordx4 v[124:125], v[100:103], off offset:256
	s_and_saveexec_b64 s[30:31], s[4:5]
	s_cbranch_execz .LBB0_1583
	v_or_b32_e32 v100, 16, v206
	v_ashrrev_i32_e32 v101, 31, v100
	s_waitcnt lgkmcnt(0)
	v_add_f32_e32 v102, v98, v99
	v_lshlrev_b64 v[98:99], 6, v[100:101]
	v_lshl_add_u64 v[98:99], s[10:11], 0, v[98:99]
	v_lshl_add_u64 v[98:99], s[8:9], 2, v[98:99]
	s_lshl_b32 s14, s44, 2
	v_lshl_add_u64 v[98:99], v[98:99], 0, s[14:15]
	global_store_dword v[98:99], v102, off
.LBB0_1583:
	s_or_b64 exec, exec, s[30:31]
	v_lshlrev_b32_e32 v98, 16, v174
	s_waitcnt lgkmcnt(0)
	v_and_b32_e32 v99, 0xffff0000, v174
	v_lshlrev_b32_e32 v100, 16, v175
	v_and_b32_e32 v101, 0xffff0000, v175
	v_lshlrev_b32_e32 v102, 16, v176
	v_and_b32_e32 v103, 0xffff0000, v176
	v_lshlrev_b32_e32 v104, 16, v177
	v_and_b32_e32 v105, 0xffff0000, v177
	v_pk_add_f32 v[96:97], v[96:97], v[100:101]
	v_pk_add_f32 v[94:95], v[94:95], v[98:99]
	v_pk_add_f32 v[98:99], v[92:93], v[104:105]
	v_pk_add_f32 v[92:93], v[90:91], v[102:103]
	v_mul_f32_e32 v90, v95, v95
	v_mul_f32_e32 v91, v97, v97
	v_fmac_f32_e32 v90, v94, v94
	v_fmac_f32_e32 v91, v96, v96
	v_add_f32_e32 v90, v90, v91
	v_mul_f32_e32 v91, v93, v93
	v_fmac_f32_e32 v91, v92, v92
	v_add_f32_e32 v90, v91, v90
	v_mul_f32_e32 v91, v99, v99
	v_fmac_f32_e32 v91, v98, v98
	v_add_f32_e32 v102, v91, v90
	v_cvt_pk_bf16_f32 v90, v94, v95
	v_cvt_pk_bf16_f32 v91, v96, v97
	v_lshlrev_b32_e32 v94, 16, v170
	v_and_b32_e32 v95, 0xffff0000, v170
	v_lshlrev_b32_e32 v96, 16, v171
	v_and_b32_e32 v97, 0xffff0000, v171
	v_cvt_pk_bf16_f32 v92, v92, v93
	v_cvt_pk_bf16_f32 v93, v98, v99
	v_lshlrev_b32_e32 v98, 16, v172
	v_and_b32_e32 v99, 0xffff0000, v172
	v_pk_add_f32 v[88:89], v[88:89], v[96:97]
	v_pk_add_f32 v[86:87], v[86:87], v[94:95]
	v_pk_add_f32 v[96:97], v[82:83], v[98:99]
	v_mul_f32_e32 v82, v87, v87
	v_mul_f32_e32 v83, v89, v89
	v_fmac_f32_e32 v82, v86, v86
	v_fmac_f32_e32 v83, v88, v88
	v_lshlrev_b32_e32 v100, 16, v173
	v_and_b32_e32 v101, 0xffff0000, v173
	v_add_f32_e32 v82, v82, v83
	v_mul_f32_e32 v83, v97, v97
	v_pk_add_f32 v[94:95], v[84:85], v[100:101]
	v_fmac_f32_e32 v83, v96, v96
	v_add_f32_e32 v82, v83, v82
	v_mul_f32_e32 v83, v95, v95
	v_fmac_f32_e32 v83, v94, v94
	v_add_f32_e32 v82, v83, v82
	v_add_f32_e32 v82, v102, v82
	v_mov_b32_e32 v83, v82
	s_nop 1
	v_permlane16_swap_b32_e32 v82, v83
	v_add_co_u32_e32 v98, vcc, s43, v122
	v_cvt_pk_bf16_f32 v84, v86, v87
	s_nop 0
	v_addc_co_u32_e32 v99, vcc, 0, v123, vcc
	s_waitcnt lgkmcnt(0)
	v_add_f32_e32 v82, v82, v83
	v_mov_b32_e32 v83, v82
	s_nop 1
	v_permlane32_swap_b32_e32 v82, v83
	v_cvt_pk_bf16_f32 v85, v88, v89
	v_cvt_pk_bf16_f32 v86, v96, v97
	v_cvt_pk_bf16_f32 v87, v94, v95
	global_store_dwordx4 v[98:99], v[90:93], off
	global_store_dwordx4 v[98:99], v[84:87], off offset:256
	s_and_saveexec_b64 s[30:31], s[4:5]
	s_cbranch_execz .LBB0_1585
	v_or_b32_e32 v84, 32, v206
	v_ashrrev_i32_e32 v85, 31, v84
	s_waitcnt lgkmcnt(0)
	v_add_f32_e32 v86, v82, v83
	v_lshlrev_b64 v[82:83], 6, v[84:85]
	v_lshl_add_u64 v[82:83], s[10:11], 0, v[82:83]
	v_lshl_add_u64 v[82:83], s[8:9], 2, v[82:83]
	s_lshl_b32 s14, s44, 2
	v_lshl_add_u64 v[82:83], v[82:83], 0, s[14:15]
	global_store_dword v[82:83], v86, off
; __device__ __forceinline__ u32x4 pack8(const f32x4 a, const f32x4 b) { u32x4 w; w.x = cvtpk(a[0], a[1]); w.y = cvtpk(a[2], a[3]); w.z = cvtpk(b[0], b[1]); w.w = cvtpk(b[2], b[3]); return w; }
; __device__ __forceinline__ void unpack8(const u32x4 w, f32x4& a, f32x4& b) { a = (f32x4){bflo(w.x), bfhi(w.x), bflo(w.y), bfhi(w.y)}; b = (f32x4){bflo(w.z), bfhi(w.z), bflo(w.w), bfhi(w.w)}; }
;     __device__ __forceinline__ void operator()(const Acc& acc, const Unit& u, int wr, int wc, int fr, int fq) const {
;     ...
;                 const int row = u.pm * BM + ai * HALF + wr * 64 + m * 16 + fr; float s = 0.f;
; #pragma unroll
;                 for (int bj = 0; bj < 2; ++bj) {
;                     const size_t off = off0 + (size_t)(ai * HALF + m * 16) * D + bj * HALF;
;                     f32x4 b0, b1; unpack8(bw[ai][m][bj], b0, b1);
;                     const f32x4 v0 = b0 + acc[ai][bj][m][0] * scale, v1 = b1 + acc[ai][bj][m][1] * scale;
;                     s += (v0[0] * v0[0] + v0[1] * v0[1]) + (v0[2] * v0[2] + v0[3] * v0[3]) + (v1[0] * v1[0] + v1[1] * v1[1]) + (v1[2] * v1[2] + v1[3] * v1[3]);
;                     if (OUT_F32) { *(f32x4*)(outf + off) = v0; *(f32x4*)(outf + off + 4) = v1; }
;                     if (OUT_BF16) *(u32x4*)(outb + off) = pack8(v0, v1);
;                 }
;                 s += __shfl_xor(s, 16); s += __shfl_xor(s, 32);
;                 if (fq == 0) ssq[(size_t)row * 16 + u.pn * 4 + wc] = s;
.LBB0_1585:
	s_or_b64 exec, exec, s[30:31]
	v_lshlrev_b32_e32 v82, 16, v166
	s_waitcnt lgkmcnt(0)
	v_and_b32_e32 v83, 0xffff0000, v166
	v_lshlrev_b32_e32 v84, 16, v167
	v_and_b32_e32 v85, 0xffff0000, v167
	v_lshlrev_b32_e32 v86, 16, v168
	v_and_b32_e32 v87, 0xffff0000, v168
	v_lshlrev_b32_e32 v88, 16, v169
	v_and_b32_e32 v89, 0xffff0000, v169
	v_pk_add_f32 v[80:81], v[80:81], v[84:85]
	v_pk_add_f32 v[78:79], v[78:79], v[82:83]
	v_pk_add_f32 v[82:83], v[76:77], v[88:89]
	v_pk_add_f32 v[76:77], v[74:75], v[86:87]
	v_mul_f32_e32 v74, v79, v79
	v_mul_f32_e32 v75, v81, v81
	v_fmac_f32_e32 v74, v78, v78
	v_fmac_f32_e32 v75, v80, v80
	v_add_f32_e32 v74, v74, v75
	v_mul_f32_e32 v75, v77, v77
	v_fmac_f32_e32 v75, v76, v76
	v_add_f32_e32 v74, v75, v74
	v_mul_f32_e32 v75, v83, v83
	v_fmac_f32_e32 v75, v82, v82
	v_add_f32_e32 v86, v75, v74
	v_cvt_pk_bf16_f32 v74, v78, v79
	v_cvt_pk_bf16_f32 v75, v80, v81
	v_lshlrev_b32_e32 v78, 16, v162
	v_and_b32_e32 v79, 0xffff0000, v162
	v_lshlrev_b32_e32 v80, 16, v163
	v_and_b32_e32 v81, 0xffff0000, v163
	v_cvt_pk_bf16_f32 v76, v76, v77
	v_cvt_pk_bf16_f32 v77, v82, v83
	v_lshlrev_b32_e32 v82, 16, v164
	v_and_b32_e32 v83, 0xffff0000, v164
	v_pk_add_f32 v[72:73], v[72:73], v[80:81]
	v_pk_add_f32 v[70:71], v[70:71], v[78:79]
	v_pk_add_f32 v[80:81], v[66:67], v[82:83]
	v_mul_f32_e32 v66, v71, v71
	v_mul_f32_e32 v67, v73, v73
	v_fmac_f32_e32 v66, v70, v70
	v_fmac_f32_e32 v67, v72, v72
	v_lshlrev_b32_e32 v84, 16, v165
	v_and_b32_e32 v85, 0xffff0000, v165
	v_add_f32_e32 v66, v66, v67
	v_mul_f32_e32 v67, v81, v81
	v_pk_add_f32 v[78:79], v[68:69], v[84:85]
	v_fmac_f32_e32 v67, v80, v80
	v_add_f32_e32 v66, v67, v66
	v_mul_f32_e32 v67, v79, v79
	v_fmac_f32_e32 v67, v78, v78
	v_add_f32_e32 v66, v67, v66
	v_add_f32_e32 v66, v86, v66
	v_mov_b32_e32 v67, v66
	s_nop 1
	v_permlane16_swap_b32_e32 v66, v67
	v_add_co_u32_e32 v82, vcc, s53, v122
	v_cvt_pk_bf16_f32 v68, v70, v71
	s_nop 0
	v_addc_co_u32_e32 v83, vcc, 0, v123, vcc
	s_waitcnt lgkmcnt(0)
	v_add_f32_e32 v66, v66, v67
	v_mov_b32_e32 v67, v66
	s_nop 1
	v_permlane32_swap_b32_e32 v66, v67
	v_cvt_pk_bf16_f32 v69, v72, v73
	v_cvt_pk_bf16_f32 v70, v80, v81
	v_cvt_pk_bf16_f32 v71, v78, v79
	global_store_dwordx4 v[82:83], v[74:77], off
	global_store_dwordx4 v[82:83], v[68:71], off offset:256
	s_and_saveexec_b64 s[30:31], s[4:5]
	s_cbranch_execz .LBB0_1587
	v_or_b32_e32 v68, 48, v206
	v_ashrrev_i32_e32 v69, 31, v68
	s_waitcnt lgkmcnt(0)
	v_add_f32_e32 v70, v66, v67
	v_lshlrev_b64 v[66:67], 6, v[68:69]
	v_lshl_add_u64 v[66:67], s[10:11], 0, v[66:67]
	v_lshl_add_u64 v[66:67], s[8:9], 2, v[66:67]
	s_lshl_b32 s14, s44, 2
	v_lshl_add_u64 v[66:67], v[66:67], 0, s[14:15]
	global_store_dword v[66:67], v70, off
.LBB0_1587:
	s_or_b64 exec, exec, s[30:31]
	v_lshlrev_b32_e32 v66, 16, v158
	s_waitcnt lgkmcnt(0)
	v_and_b32_e32 v67, 0xffff0000, v158
	v_lshlrev_b32_e32 v68, 16, v159
	v_and_b32_e32 v69, 0xffff0000, v159
	v_lshlrev_b32_e32 v70, 16, v160
	v_and_b32_e32 v71, 0xffff0000, v160
	v_lshlrev_b32_e32 v72, 16, v161
	v_and_b32_e32 v73, 0xffff0000, v161
	v_pk_add_f32 v[64:65], v[64:65], v[68:69]
	v_pk_add_f32 v[62:63], v[62:63], v[66:67]
	v_pk_add_f32 v[66:67], v[60:61], v[72:73]
	v_pk_add_f32 v[60:61], v[58:59], v[70:71]
	v_mul_f32_e32 v58, v63, v63
	v_mul_f32_e32 v59, v65, v65
	v_fmac_f32_e32 v58, v62, v62
	v_fmac_f32_e32 v59, v64, v64
	v_add_f32_e32 v58, v58, v59
	v_mul_f32_e32 v59, v61, v61
	v_fmac_f32_e32 v59, v60, v60
	v_add_f32_e32 v58, v59, v58
	v_mul_f32_e32 v59, v67, v67
	v_fmac_f32_e32 v59, v66, v66
	v_add_f32_e32 v70, v59, v58
	v_cvt_pk_bf16_f32 v58, v62, v63
	v_cvt_pk_bf16_f32 v59, v64, v65
	v_lshlrev_b32_e32 v62, 16, v154
	v_and_b32_e32 v63, 0xffff0000, v154
	v_lshlrev_b32_e32 v64, 16, v155
	v_and_b32_e32 v65, 0xffff0000, v155
	v_cvt_pk_bf16_f32 v60, v60, v61
	v_cvt_pk_bf16_f32 v61, v66, v67
	v_lshlrev_b32_e32 v66, 16, v156
	v_and_b32_e32 v67, 0xffff0000, v156
	v_pk_add_f32 v[56:57], v[56:57], v[64:65]
	v_pk_add_f32 v[54:55], v[54:55], v[62:63]
	v_pk_add_f32 v[64:65], v[50:51], v[66:67]
	v_mul_f32_e32 v50, v55, v55
	v_mul_f32_e32 v51, v57, v57
	v_fmac_f32_e32 v50, v54, v54
	v_fmac_f32_e32 v51, v56, v56
	v_lshlrev_b32_e32 v68, 16, v157
	v_and_b32_e32 v69, 0xffff0000, v157
	v_add_f32_e32 v50, v50, v51
	v_mul_f32_e32 v51, v65, v65
	v_pk_add_f32 v[62:63], v[52:53], v[68:69]
	v_fmac_f32_e32 v51, v64, v64
	v_add_f32_e32 v50, v51, v50
	v_mul_f32_e32 v51, v63, v63
	v_fmac_f32_e32 v51, v62, v62
	v_add_f32_e32 v50, v51, v50
	v_add_f32_e32 v50, v70, v50
	v_mov_b32_e32 v51, v50
	s_nop 1
	v_permlane16_swap_b32_e32 v50, v51
	v_add_co_u32_e32 v66, vcc, s59, v122
	v_cvt_pk_bf16_f32 v52, v54, v55
	s_nop 0
	v_addc_co_u32_e32 v67, vcc, 0, v123, vcc
	s_waitcnt lgkmcnt(0)
	v_add_f32_e32 v50, v50, v51
	v_mov_b32_e32 v51, v50
	s_nop 1
	v_permlane32_swap_b32_e32 v50, v51
	v_cvt_pk_bf16_f32 v53, v56, v57
	v_cvt_pk_bf16_f32 v54, v64, v65
	v_cvt_pk_bf16_f32 v55, v62, v63
	global_store_dwordx4 v[66:67], v[58:61], off
	global_store_dwordx4 v[66:67], v[52:55], off offset:256
	s_and_saveexec_b64 s[30:31], s[4:5]
	s_cbranch_execz .LBB0_1589
	v_add_u32_e32 v52, 0x80, v206
	v_ashrrev_i32_e32 v53, 31, v52
	s_waitcnt lgkmcnt(0)
	v_add_f32_e32 v54, v50, v51
	v_lshlrev_b64 v[50:51], 6, v[52:53]
	v_lshl_add_u64 v[50:51], s[10:11], 0, v[50:51]
	v_lshl_add_u64 v[50:51], s[8:9], 2, v[50:51]
	s_lshl_b32 s14, s44, 2
	v_lshl_add_u64 v[50:51], v[50:51], 0, s[14:15]
	global_store_dword v[50:51], v54, off
; __device__ __forceinline__ u32x4 pack8(const f32x4 a, const f32x4 b) { u32x4 w; w.x = cvtpk(a[0], a[1]); w.y = cvtpk(a[2], a[3]); w.z = cvtpk(b[0], b[1]); w.w = cvtpk(b[2], b[3]); return w; }
; __device__ __forceinline__ void unpack8(const u32x4 w, f32x4& a, f32x4& b) { a = (f32x4){bflo(w.x), bfhi(w.x), bflo(w.y), bfhi(w.y)}; b = (f32x4){bflo(w.z), bfhi(w.z), bflo(w.w), bfhi(w.w)}; }
;     __device__ __forceinline__ void operator()(const Acc& acc, const Unit& u, int wr, int wc, int fr, int fq) const {
;     ...
;                 const int row = u.pm * BM + ai * HALF + wr * 64 + m * 16 + fr; float s = 0.f;
; #pragma unroll
;                 for (int bj = 0; bj < 2; ++bj) {
;                     const size_t off = off0 + (size_t)(ai * HALF + m * 16) * D + bj * HALF;
;                     f32x4 b0, b1; unpack8(bw[ai][m][bj], b0, b1);
;                     const f32x4 v0 = b0 + acc[ai][bj][m][0] * scale, v1 = b1 + acc[ai][bj][m][1] * scale;
;                     s += (v0[0] * v0[0] + v0[1] * v0[1]) + (v0[2] * v0[2] + v0[3] * v0[3]) + (v1[0] * v1[0] + v1[1] * v1[1]) + (v1[2] * v1[2] + v1[3] * v1[3]);
;                     if (OUT_F32) { *(f32x4*)(outf + off) = v0; *(f32x4*)(outf + off + 4) = v1; }
;                     if (OUT_BF16) *(u32x4*)(outb + off) = pack8(v0, v1);
;                 }
;                 s += __shfl_xor(s, 16); s += __shfl_xor(s, 32);
;                 if (fq == 0) ssq[(size_t)row * 16 + u.pn * 4 + wc] = s;
.LBB0_1589:
	s_or_b64 exec, exec, s[30:31]
	v_lshlrev_b32_e32 v50, 16, v150
	s_waitcnt lgkmcnt(0)
	v_and_b32_e32 v51, 0xffff0000, v150
	v_lshlrev_b32_e32 v52, 16, v151
	v_and_b32_e32 v53, 0xffff0000, v151
	v_lshlrev_b32_e32 v54, 16, v152
	v_and_b32_e32 v55, 0xffff0000, v152
	v_lshlrev_b32_e32 v56, 16, v153
	v_and_b32_e32 v57, 0xffff0000, v153
	v_pk_add_f32 v[48:49], v[48:49], v[52:53]
	v_pk_add_f32 v[46:47], v[46:47], v[50:51]
	v_pk_add_f32 v[50:51], v[44:45], v[56:57]
	v_pk_add_f32 v[44:45], v[42:43], v[54:55]
	v_mul_f32_e32 v42, v47, v47
	v_mul_f32_e32 v43, v49, v49
	v_fmac_f32_e32 v42, v46, v46
	v_fmac_f32_e32 v43, v48, v48
	v_add_f32_e32 v42, v42, v43
	v_mul_f32_e32 v43, v45, v45
	v_fmac_f32_e32 v43, v44, v44
	v_add_f32_e32 v42, v43, v42
	v_mul_f32_e32 v43, v51, v51
	v_fmac_f32_e32 v43, v50, v50
	v_add_f32_e32 v54, v43, v42
	v_cvt_pk_bf16_f32 v42, v46, v47
	v_cvt_pk_bf16_f32 v43, v48, v49
	v_lshlrev_b32_e32 v46, 16, v146
	v_and_b32_e32 v47, 0xffff0000, v146
	v_lshlrev_b32_e32 v48, 16, v147
	v_and_b32_e32 v49, 0xffff0000, v147
	v_cvt_pk_bf16_f32 v44, v44, v45
	v_cvt_pk_bf16_f32 v45, v50, v51
	v_lshlrev_b32_e32 v50, 16, v148
	v_and_b32_e32 v51, 0xffff0000, v148
	v_pk_add_f32 v[40:41], v[40:41], v[48:49]
	v_pk_add_f32 v[38:39], v[38:39], v[46:47]
	v_pk_add_f32 v[48:49], v[34:35], v[50:51]
	v_mul_f32_e32 v34, v39, v39
	v_mul_f32_e32 v35, v41, v41
	v_fmac_f32_e32 v34, v38, v38
	v_fmac_f32_e32 v35, v40, v40
	v_lshlrev_b32_e32 v52, 16, v149
	v_and_b32_e32 v53, 0xffff0000, v149
	v_add_f32_e32 v34, v34, v35
	v_mul_f32_e32 v35, v49, v49
	v_pk_add_f32 v[46:47], v[36:37], v[52:53]
	v_fmac_f32_e32 v35, v48, v48
	v_add_f32_e32 v34, v35, v34
	v_mul_f32_e32 v35, v47, v47
	v_fmac_f32_e32 v35, v46, v46
	v_add_f32_e32 v34, v35, v34
	v_add_f32_e32 v34, v54, v34
	v_mov_b32_e32 v35, v34
	s_nop 1
	v_permlane16_swap_b32_e32 v34, v35
	v_add_co_u32_e32 v50, vcc, s60, v122
	v_cvt_pk_bf16_f32 v36, v38, v39
	s_nop 0
	v_addc_co_u32_e32 v51, vcc, 0, v123, vcc
	s_waitcnt lgkmcnt(0)
	v_add_f32_e32 v34, v34, v35
	v_mov_b32_e32 v35, v34
	s_nop 1
	v_permlane32_swap_b32_e32 v34, v35
	v_cvt_pk_bf16_f32 v37, v40, v41
	v_cvt_pk_bf16_f32 v38, v48, v49
	v_cvt_pk_bf16_f32 v39, v46, v47
	global_store_dwordx4 v[50:51], v[42:45], off
	global_store_dwordx4 v[50:51], v[36:39], off offset:256
	s_and_saveexec_b64 s[30:31], s[4:5]
	s_cbranch_execz .LBB0_1591
	v_add_u32_e32 v36, 0x90, v206
	v_ashrrev_i32_e32 v37, 31, v36
	s_waitcnt lgkmcnt(0)
	v_add_f32_e32 v38, v34, v35
	v_lshlrev_b64 v[34:35], 6, v[36:37]
	v_lshl_add_u64 v[34:35], s[10:11], 0, v[34:35]
	v_lshl_add_u64 v[34:35], s[8:9], 2, v[34:35]
	s_lshl_b32 s14, s44, 2
	v_lshl_add_u64 v[34:35], v[34:35], 0, s[14:15]
	global_store_dword v[34:35], v38, off
; __device__ __forceinline__ u32x4 pack8(const f32x4 a, const f32x4 b) { u32x4 w; w.x = cvtpk(a[0], a[1]); w.y = cvtpk(a[2], a[3]); w.z = cvtpk(b[0], b[1]); w.w = cvtpk(b[2], b[3]); return w; }
; __device__ __forceinline__ void unpack8(const u32x4 w, f32x4& a, f32x4& b) { a = (f32x4){bflo(w.x), bfhi(w.x), bflo(w.y), bfhi(w.y)}; b = (f32x4){bflo(w.z), bfhi(w.z), bflo(w.w), bfhi(w.w)}; }
;     __device__ __forceinline__ void operator()(const Acc& acc, const Unit& u, int wr, int wc, int fr, int fq) const {
;     ...
;                 const int row = u.pm * BM + ai * HALF + wr * 64 + m * 16 + fr; float s = 0.f;
; #pragma unroll
;                 for (int bj = 0; bj < 2; ++bj) {
;                     const size_t off = off0 + (size_t)(ai * HALF + m * 16) * D + bj * HALF;
;                     f32x4 b0, b1; unpack8(bw[ai][m][bj], b0, b1);
;                     const f32x4 v0 = b0 + acc[ai][bj][m][0] * scale, v1 = b1 + acc[ai][bj][m][1] * scale;
;                     s += (v0[0] * v0[0] + v0[1] * v0[1]) + (v0[2] * v0[2] + v0[3] * v0[3]) + (v1[0] * v1[0] + v1[1] * v1[1]) + (v1[2] * v1[2] + v1[3] * v1[3]);
;                     if (OUT_F32) { *(f32x4*)(outf + off) = v0; *(f32x4*)(outf + off + 4) = v1; }
;                     if (OUT_BF16) *(u32x4*)(outb + off) = pack8(v0, v1);
;                 }
;                 s += __shfl_xor(s, 16); s += __shfl_xor(s, 32);
;                 if (fq == 0) ssq[(size_t)row * 16 + u.pn * 4 + wc] = s;
.LBB0_1591:
	s_or_b64 exec, exec, s[30:31]
	v_lshlrev_b32_e32 v34, 16, v134
	s_waitcnt lgkmcnt(0)
	v_and_b32_e32 v35, 0xffff0000, v134
	v_lshlrev_b32_e32 v36, 16, v135
	v_and_b32_e32 v37, 0xffff0000, v135
	v_lshlrev_b32_e32 v38, 16, v136
	v_and_b32_e32 v39, 0xffff0000, v136
	v_lshlrev_b32_e32 v40, 16, v137
	v_and_b32_e32 v41, 0xffff0000, v137
	v_pk_add_f32 v[32:33], v[32:33], v[36:37]
	v_pk_add_f32 v[30:31], v[30:31], v[34:35]
	v_pk_add_f32 v[34:35], v[28:29], v[40:41]
	v_pk_add_f32 v[28:29], v[26:27], v[38:39]
	v_mul_f32_e32 v26, v31, v31
	v_mul_f32_e32 v27, v33, v33
	v_fmac_f32_e32 v26, v30, v30
	v_fmac_f32_e32 v27, v32, v32
	v_add_f32_e32 v26, v26, v27
	v_mul_f32_e32 v27, v29, v29
	v_fmac_f32_e32 v27, v28, v28
	v_add_f32_e32 v26, v27, v26
	v_mul_f32_e32 v27, v35, v35
	v_fmac_f32_e32 v27, v34, v34
	v_add_f32_e32 v38, v27, v26
	v_cvt_pk_bf16_f32 v26, v30, v31
	v_cvt_pk_bf16_f32 v27, v32, v33
	v_lshlrev_b32_e32 v30, 16, v130
	v_and_b32_e32 v31, 0xffff0000, v130
	v_lshlrev_b32_e32 v32, 16, v131
	v_and_b32_e32 v33, 0xffff0000, v131
	v_cvt_pk_bf16_f32 v28, v28, v29
	v_cvt_pk_bf16_f32 v29, v34, v35
	v_lshlrev_b32_e32 v34, 16, v132
	v_and_b32_e32 v35, 0xffff0000, v132
	v_pk_add_f32 v[24:25], v[24:25], v[32:33]
	v_pk_add_f32 v[22:23], v[22:23], v[30:31]
	v_pk_add_f32 v[32:33], v[18:19], v[34:35]
	v_mul_f32_e32 v18, v23, v23
	v_mul_f32_e32 v19, v25, v25
	v_fmac_f32_e32 v18, v22, v22
	v_fmac_f32_e32 v19, v24, v24
	v_lshlrev_b32_e32 v36, 16, v133
	v_and_b32_e32 v37, 0xffff0000, v133
	v_add_f32_e32 v18, v18, v19
	v_mul_f32_e32 v19, v33, v33
	v_pk_add_f32 v[30:31], v[20:21], v[36:37]
	v_fmac_f32_e32 v19, v32, v32
	v_add_f32_e32 v18, v19, v18
	v_mul_f32_e32 v19, v31, v31
	v_fmac_f32_e32 v19, v30, v30
	v_add_f32_e32 v18, v19, v18
	v_add_f32_e32 v18, v38, v18
	v_mov_b32_e32 v19, v18
	s_nop 1
	v_permlane16_swap_b32_e32 v18, v19
	v_add_co_u32_e32 v34, vcc, s61, v122
	v_cvt_pk_bf16_f32 v20, v22, v23
	s_nop 0
	v_addc_co_u32_e32 v35, vcc, 0, v123, vcc
	s_waitcnt lgkmcnt(0)
	v_add_f32_e32 v18, v18, v19
	v_mov_b32_e32 v19, v18
	s_nop 1
	v_permlane32_swap_b32_e32 v18, v19
	v_cvt_pk_bf16_f32 v21, v24, v25
	v_cvt_pk_bf16_f32 v22, v32, v33
	v_cvt_pk_bf16_f32 v23, v30, v31
	global_store_dwordx4 v[34:35], v[26:29], off
	global_store_dwordx4 v[34:35], v[20:23], off offset:256
	s_and_saveexec_b64 s[30:31], s[4:5]
	s_cbranch_execz .LBB0_1593
	v_add_u32_e32 v20, 0xa0, v206
	v_ashrrev_i32_e32 v21, 31, v20
	s_waitcnt lgkmcnt(0)
	v_add_f32_e32 v22, v18, v19
	v_lshlrev_b64 v[18:19], 6, v[20:21]
	v_lshl_add_u64 v[18:19], s[10:11], 0, v[18:19]
	v_lshl_add_u64 v[18:19], s[8:9], 2, v[18:19]
	s_lshl_b32 s14, s44, 2
	v_lshl_add_u64 v[18:19], v[18:19], 0, s[14:15]
	global_store_dword v[18:19], v22, off
.LBB0_1593:
	s_or_b64 exec, exec, s[30:31]
	v_lshlrev_b32_e32 v18, 16, v114
	s_waitcnt lgkmcnt(0)
	v_and_b32_e32 v19, 0xffff0000, v114
	v_lshlrev_b32_e32 v20, 16, v115
	v_and_b32_e32 v21, 0xffff0000, v115
	v_lshlrev_b32_e32 v22, 16, v116
	v_and_b32_e32 v23, 0xffff0000, v116
	v_lshlrev_b32_e32 v24, 16, v117
	v_and_b32_e32 v25, 0xffff0000, v117
	v_pk_add_f32 v[16:17], v[16:17], v[20:21]
	v_pk_add_f32 v[14:15], v[14:15], v[18:19]
	v_pk_add_f32 v[18:19], v[12:13], v[24:25]
	v_pk_add_f32 v[12:13], v[10:11], v[22:23]
	v_mul_f32_e32 v10, v15, v15
	v_mul_f32_e32 v11, v17, v17
	v_fmac_f32_e32 v10, v14, v14
	v_fmac_f32_e32 v11, v16, v16
	v_add_f32_e32 v10, v10, v11
	v_mul_f32_e32 v11, v13, v13
	v_fmac_f32_e32 v11, v12, v12
	v_add_f32_e32 v10, v11, v10
	v_mul_f32_e32 v11, v19, v19
	v_fmac_f32_e32 v11, v18, v18
	v_add_f32_e32 v22, v11, v10
	v_cvt_pk_bf16_f32 v10, v14, v15
	v_cvt_pk_bf16_f32 v11, v16, v17
	v_lshlrev_b32_e32 v14, 16, v106
	v_and_b32_e32 v15, 0xffff0000, v106
	v_lshlrev_b32_e32 v16, 16, v107
	v_and_b32_e32 v17, 0xffff0000, v107
	v_cvt_pk_bf16_f32 v12, v12, v13
	v_cvt_pk_bf16_f32 v13, v18, v19
	v_lshlrev_b32_e32 v18, 16, v108
	v_and_b32_e32 v19, 0xffff0000, v108
	v_pk_add_f32 v[8:9], v[8:9], v[16:17]
	v_pk_add_f32 v[6:7], v[6:7], v[14:15]
	v_pk_add_f32 v[16:17], v[2:3], v[18:19]
	v_mul_f32_e32 v2, v7, v7
	v_mul_f32_e32 v3, v9, v9
	v_fmac_f32_e32 v2, v6, v6
	v_fmac_f32_e32 v3, v8, v8
	v_lshlrev_b32_e32 v20, 16, v109
	v_and_b32_e32 v21, 0xffff0000, v109
	v_add_f32_e32 v2, v2, v3
	v_mul_f32_e32 v3, v17, v17
	v_pk_add_f32 v[14:15], v[4:5], v[20:21]
	v_fmac_f32_e32 v3, v16, v16
	v_add_f32_e32 v2, v3, v2
	v_mul_f32_e32 v3, v15, v15
	v_fmac_f32_e32 v3, v14, v14
	v_add_f32_e32 v2, v3, v2
	v_add_f32_e32 v2, v22, v2
	v_mov_b32_e32 v3, v2
	s_nop 1
	v_permlane16_swap_b32_e32 v2, v3
	v_add_co_u32_e32 v18, vcc, s62, v122
	v_cvt_pk_bf16_f32 v4, v6, v7
	s_nop 0
	v_addc_co_u32_e32 v19, vcc, 0, v123, vcc
	s_waitcnt lgkmcnt(0)
	v_add_f32_e32 v2, v2, v3
	v_mov_b32_e32 v3, v2
	s_nop 1
	v_permlane32_swap_b32_e32 v2, v3
	v_cvt_pk_bf16_f32 v5, v8, v9
	v_cvt_pk_bf16_f32 v6, v16, v17
	v_cvt_pk_bf16_f32 v7, v14, v15
	global_store_dwordx4 v[18:19], v[10:13], off
	global_store_dwordx4 v[18:19], v[4:7], off offset:256
	s_and_saveexec_b64 s[30:31], s[4:5]
	s_cbranch_execz .LBB0_1595
	v_add_u32_e32 v4, 0xb0, v206
	v_ashrrev_i32_e32 v5, 31, v4
	s_waitcnt lgkmcnt(0)
	v_add_f32_e32 v6, v2, v3
	v_lshlrev_b64 v[2:3], 6, v[4:5]
	v_lshl_add_u64 v[2:3], s[10:11], 0, v[2:3]
	v_lshl_add_u64 v[2:3], s[8:9], 2, v[2:3]
	s_lshl_b32 s14, s44, 2
	v_lshl_add_u64 v[2:3], v[2:3], 0, s[14:15]
	global_store_dword v[2:3], v6, off

; __device__ __forceinline__ void unpack8(const u32x4 w, f32x4& a, f32x4& b) { a = (f32x4){bflo(w.x), bfhi(w.x), bflo(w.y), bfhi(w.y)}; b = (f32x4){bflo(w.z), bfhi(w.z), bflo(w.w), bfhi(w.w)}; }
;     __device__ __forceinline__ void fused(Acc& acc, const Unit& u, int wr, int wc, int fr, int fq, LAS unsigned char* lds) const {
;     ...
; #pragma unroll
;         for (int ai = 0; ai < 2; ++ai)
; #pragma unroll
;             for (int m = 0; m < 4; ++m) {
;                 const int rt = ai * HALF + wr * 64 + m * 16 + fr; const int row = u.pm * BM + rt; float s = 0.f;
; #pragma unroll
;                 for (int bj = 0; bj < 2; ++bj) {
;                     const size_t off = (size_t)row * D + u.pn * BM + bj * HALF + wc * 32 + 8 * fq;
;                     f32x4 b0, b1; unpack8(*(const u32x4*)(base + off), b0, b1);
;                     const f32x4 v0 = b0 + acc[ai][bj][m][0] * scale, v1 = b1 + acc[ai][bj][m][1] * scale;
;                     acc[ai][bj][m][0] = v0; acc[ai][bj][m][1] = v1;
;                     s += (v0[0] * v0[0] + v0[1] * v0[1]) + (v0[2] * v0[2] + v0[3] * v0[3]) + (v1[0] * v1[0] + v1[1] * v1[1]) + (v1[2] * v1[2] + v1[3] * v1[3]);
;                 }
;                 s += __shfl_xor(s, 16); s += __shfl_xor(s, 32);
;                 if (fq == 0) Pw[rt * 4 + wc] = s;
.LBB0_1894:
	s_lshl_b32 s8, s10, 8
	v_add_u32_e32 v134, s8, v167
	v_ashrrev_i32_e32 v135, 31, v134
	s_lshl_b32 s2, s12, 8
	v_lshlrev_b64 v[136:137], 11, v[134:135]
	s_ashr_i32 s3, s2, 31
	v_lshl_add_u64 v[136:137], s[40:41], 0, v[136:137]
	s_mov_b32 s1, 0
	v_lshl_add_u64 v[136:137], s[2:3], 1, v[136:137]
	s_lshl_b32 s0, s11, 6
	v_mov_b32_e32 v133, 0
	v_lshl_add_u64 v[136:137], v[136:137], 0, s[0:1]
	v_lshl_add_u64 v[140:141], v[136:137], 0, v[132:133]
	s_waitcnt vmcnt(0)
	s_barrier
	v_mov_b64_e32 v[196:197], v[140:141]
	global_load_dwordx4 v[136:139], v[140:141], off
	s_nop 0
	global_load_dwordx4 v[140:143], v[140:141], off offset:256
	s_mov_b64 s[100:101], 0x8000
	v_lshl_add_u64 v[254:255], v[196:197], 0, s[100:101]
	global_load_dwordx4 v[192:195], v[254:255], off
	global_load_dwordx4 v[200:203], v[254:255], off offset:256
	s_mov_b64 s[100:101], 0x10000
	v_lshl_add_u64 v[254:255], v[196:197], 0, s[100:101]
	global_load_dwordx4 v[204:207], v[254:255], off
	global_load_dwordx4 v[208:211], v[254:255], off offset:256
	s_mov_b64 s[100:101], 0x18000
	v_lshl_add_u64 v[254:255], v[196:197], 0, s[100:101]
	global_load_dwordx4 v[212:215], v[254:255], off
	global_load_dwordx4 v[216:219], v[254:255], off offset:256
	s_mov_b64 s[100:101], 0x40000
	v_lshl_add_u64 v[254:255], v[196:197], 0, s[100:101]
	global_load_dwordx4 v[220:223], v[254:255], off
	global_load_dwordx4 v[224:227], v[254:255], off offset:256
	s_mov_b64 s[100:101], 0x48000
	v_lshl_add_u64 v[254:255], v[196:197], 0, s[100:101]
	global_load_dwordx4 v[228:231], v[254:255], off
	global_load_dwordx4 v[232:235], v[254:255], off offset:256
	s_mov_b64 s[100:101], 0x50000
	v_lshl_add_u64 v[254:255], v[196:197], 0, s[100:101]
	global_load_dwordx4 v[236:239], v[254:255], off
	global_load_dwordx4 v[240:243], v[254:255], off offset:256
	s_mov_b64 s[100:101], 0x58000
	v_lshl_add_u64 v[254:255], v[196:197], 0, s[100:101]
	global_load_dwordx4 v[244:247], v[254:255], off
	global_load_dwordx4 v[248:251], v[254:255], off offset:256
	v_mbcnt_lo_u32_b32 v132, -1, 0
	v_mbcnt_hi_u32_b32 v132, -1, v132
	v_and_b32_e32 v145, 64, v132
	v_xor_b32_e32 v144, 16, v132
	v_add_u32_e32 v152, 64, v145
	v_cmp_lt_i32_e32 vcc, v144, v152
	s_lshl_b32 s0, s11, 2
	v_lshlrev_b32_e32 v164, 3, v154
	v_cndmask_b32_e32 v144, v132, v144, vcc
	v_lshlrev_b32_e32 v165, 2, v144
	s_lshl_b32 s22, s11, 5
	s_add_i32 s9, s0, 0
	s_waitcnt vmcnt(14)
	v_lshlrev_b32_e32 v144, 16, v136
	v_and_b32_e32 v145, 0xffff0000, v136
	v_lshlrev_b32_e32 v136, 16, v137
	v_and_b32_e32 v137, 0xffff0000, v137
	v_lshlrev_b32_e32 v148, 16, v140
	v_and_b32_e32 v149, 0xffff0000, v140
	v_lshlrev_b32_e32 v140, 16, v141
	v_and_b32_e32 v141, 0xffff0000, v141
	v_lshlrev_b32_e32 v146, 16, v138
	v_and_b32_e32 v147, 0xffff0000, v138
	v_lshlrev_b32_e32 v150, 16, v142
	v_and_b32_e32 v151, 0xffff0000, v142
	v_pk_fma_f32 v[128:129], v[128:129], 0.5, v[136:137] op_sel_hi:[1,0,1]
	v_pk_fma_f32 v[126:127], v[126:127], 0.5, v[144:145] op_sel_hi:[1,0,1]
	v_pk_fma_f32 v[120:121], v[120:121], 0.5, v[140:141] op_sel_hi:[1,0,1]
	v_pk_fma_f32 v[118:119], v[118:119], 0.5, v[148:149] op_sel_hi:[1,0,1]
	v_lshlrev_b32_e32 v138, 16, v139
	v_and_b32_e32 v139, 0xffff0000, v139
	v_lshlrev_b32_e32 v142, 16, v143
	v_and_b32_e32 v143, 0xffff0000, v143
	v_pk_fma_f32 v[122:123], v[122:123], 0.5, v[146:147] op_sel_hi:[1,0,1]
	v_pk_fma_f32 v[114:115], v[114:115], 0.5, v[150:151] op_sel_hi:[1,0,1]
	v_mul_f32_e32 v136, v127, v127
	v_mul_f32_e32 v137, v129, v129
	v_mul_f32_e32 v140, v119, v119
	v_mul_f32_e32 v141, v121, v121
	v_pk_fma_f32 v[124:125], v[124:125], 0.5, v[138:139] op_sel_hi:[1,0,1]
	v_pk_fma_f32 v[116:117], v[116:117], 0.5, v[142:143] op_sel_hi:[1,0,1]
	v_mul_f32_e32 v138, v123, v123
	v_mul_f32_e32 v142, v115, v115
	v_fmac_f32_e32 v136, v126, v126
	v_fmac_f32_e32 v137, v128, v128
	v_fmac_f32_e32 v140, v118, v118
	v_fmac_f32_e32 v141, v120, v120
	v_mul_f32_e32 v139, v125, v125
	v_mul_f32_e32 v143, v117, v117
	v_fmac_f32_e32 v138, v122, v122
	v_fmac_f32_e32 v142, v114, v114
	v_add_f32_e32 v136, v136, v137
	v_add_f32_e32 v137, v140, v141
	v_fmac_f32_e32 v139, v124, v124
	v_fmac_f32_e32 v143, v116, v116
	v_add_f32_e32 v136, v138, v136
	v_add_f32_e32 v137, v142, v137
	v_add_f32_e32 v136, v139, v136
	v_add_f32_e32 v137, v143, v137
	v_add_f32_e32 v136, v136, v137
	v_mov_b32_e32 v137, v136
	s_nop 1
	v_permlane16_swap_b32_e32 v136, v137
	v_xor_b32_e32 v138, 32, v132
	v_cmp_lt_i32_e32 vcc, v138, v152
	s_nop 1
	v_cndmask_b32_e32 v132, v132, v138, vcc
	v_lshlrev_b32_e32 v168, 2, v132
	s_waitcnt lgkmcnt(0)
	v_add_f32_e32 v132, v136, v137
	v_mov_b32_e32 v136, v132
	s_nop 1
	v_permlane32_swap_b32_e32 v132, v136
	v_cmp_eq_u32_e32 vcc, 0, v154
	s_and_saveexec_b64 s[6:7], vcc
	s_cbranch_execz .LBB0_1896
	v_lshl_add_u32 v137, v167, 4, s9
	s_waitcnt lgkmcnt(0)
	v_add_f32_e32 v132, v132, v136
	ds_write_b32 v137, v132
; __device__ __forceinline__ void unpack8(const u32x4 w, f32x4& a, f32x4& b) { a = (f32x4){bflo(w.x), bfhi(w.x), bflo(w.y), bfhi(w.y)}; b = (f32x4){bflo(w.z), bfhi(w.z), bflo(w.w), bfhi(w.w)}; }
;     __device__ __forceinline__ void fused(Acc& acc, const Unit& u, int wr, int wc, int fr, int fq, LAS unsigned char* lds) const {
;     ...
; #pragma unroll
;         for (int ai = 0; ai < 2; ++ai)
; #pragma unroll
;             for (int m = 0; m < 4; ++m) {
;                 const int rt = ai * HALF + wr * 64 + m * 16 + fr; const int row = u.pm * BM + rt; float s = 0.f;
; #pragma unroll
;                 for (int bj = 0; bj < 2; ++bj) {
;                     const size_t off = (size_t)row * D + u.pn * BM + bj * HALF + wc * 32 + 8 * fq;
;                     f32x4 b0, b1; unpack8(*(const u32x4*)(base + off), b0, b1);
;                     const f32x4 v0 = b0 + acc[ai][bj][m][0] * scale, v1 = b1 + acc[ai][bj][m][1] * scale;
;                     acc[ai][bj][m][0] = v0; acc[ai][bj][m][1] = v1;
;                     s += (v0[0] * v0[0] + v0[1] * v0[1]) + (v0[2] * v0[2] + v0[3] * v0[3]) + (v1[0] * v1[0] + v1[1] * v1[1]) + (v1[2] * v1[2] + v1[3] * v1[3]);
;                 }
;                 s += __shfl_xor(s, 16); s += __shfl_xor(s, 32);
;                 if (fq == 0) Pw[rt * 4 + wc] = s;
.LBB0_1896:
	s_or_b64 exec, exec, s[6:7]
	v_or_b32_e32 v138, 16, v167
	s_waitcnt lgkmcnt(0)
	v_add_u32_e32 v136, s8, v138
	v_ashrrev_i32_e32 v137, 31, v136
	v_lshlrev_b64 v[140:141], 11, v[136:137]
	v_lshl_add_u64 v[140:141], s[40:41], 0, v[140:141]
	v_lshl_add_u64 v[140:141], s[2:3], 1, v[140:141]
	s_lshl_b32 s0, s22, 1
	v_lshl_add_u64 v[140:141], v[140:141], 0, s[0:1]
	v_lshlrev_b32_e32 v132, 1, v164
	v_lshl_add_u64 v[144:145], v[140:141], 0, v[132:133]
	s_nop 0
	s_waitcnt vmcnt(13)
	v_lshlrev_b32_e32 v148, 16, v192
	v_and_b32_e32 v149, 0xffff0000, v192
	v_lshlrev_b32_e32 v140, 16, v193
	v_and_b32_e32 v141, 0xffff0000, v193
	s_waitcnt vmcnt(12)
	v_lshlrev_b32_e32 v152, 16, v200
	v_and_b32_e32 v153, 0xffff0000, v200
	v_lshlrev_b32_e32 v144, 16, v201
	v_and_b32_e32 v145, 0xffff0000, v201
	v_lshlrev_b32_e32 v150, 16, v194
	v_and_b32_e32 v151, 0xffff0000, v194
	v_lshlrev_b32_e32 v142, 16, v195
	v_and_b32_e32 v143, 0xffff0000, v195
	v_lshlrev_b32_e32 v154, 16, v202
	v_and_b32_e32 v155, 0xffff0000, v202
	v_pk_fma_f32 v[112:113], v[112:113], 0.5, v[140:141] op_sel_hi:[1,0,1]
	v_pk_fma_f32 v[110:111], v[110:111], 0.5, v[148:149] op_sel_hi:[1,0,1]
	v_pk_fma_f32 v[104:105], v[104:105], 0.5, v[144:145] op_sel_hi:[1,0,1]
	v_pk_fma_f32 v[102:103], v[102:103], 0.5, v[152:153] op_sel_hi:[1,0,1]
	v_lshlrev_b32_e32 v146, 16, v203
	v_and_b32_e32 v147, 0xffff0000, v203
	v_pk_fma_f32 v[108:109], v[108:109], 0.5, v[142:143] op_sel_hi:[1,0,1]
	v_pk_fma_f32 v[106:107], v[106:107], 0.5, v[150:151] op_sel_hi:[1,0,1]
	v_pk_fma_f32 v[98:99], v[98:99], 0.5, v[154:155] op_sel_hi:[1,0,1]
	v_mul_f32_e32 v133, v111, v111
	v_mul_f32_e32 v139, v113, v113
	v_mul_f32_e32 v142, v103, v103
	v_mul_f32_e32 v143, v105, v105
	v_pk_fma_f32 v[100:101], v[100:101], 0.5, v[146:147] op_sel_hi:[1,0,1]
	v_mul_f32_e32 v140, v107, v107
	v_mul_f32_e32 v144, v99, v99
	v_fmac_f32_e32 v133, v110, v110
	v_fmac_f32_e32 v139, v112, v112
	v_fmac_f32_e32 v142, v102, v102
	v_fmac_f32_e32 v143, v104, v104
	v_mul_f32_e32 v141, v109, v109
	v_mul_f32_e32 v145, v101, v101
	v_fmac_f32_e32 v140, v106, v106
	v_fmac_f32_e32 v144, v98, v98
	v_add_f32_e32 v133, v133, v139
	v_add_f32_e32 v139, v142, v143
	v_fmac_f32_e32 v141, v108, v108
	v_fmac_f32_e32 v145, v100, v100
	v_add_f32_e32 v133, v140, v133
	v_add_f32_e32 v139, v144, v139
	v_add_f32_e32 v133, v141, v133
	v_add_f32_e32 v139, v145, v139
	v_add_f32_e32 v133, v133, v139
	v_mov_b32_e32 v139, v133
	s_nop 1
	v_permlane16_swap_b32_e32 v133, v139
	s_waitcnt lgkmcnt(0)
	v_add_f32_e32 v133, v133, v139
	v_mov_b32_e32 v139, v133
	s_nop 1
	v_permlane32_swap_b32_e32 v133, v139
	s_and_saveexec_b64 s[6:7], vcc
	s_cbranch_execz .LBB0_1898
	v_lshl_add_u32 v138, v138, 4, s9
	s_waitcnt lgkmcnt(0)
	v_add_f32_e32 v133, v133, v139
	ds_write_b32 v138, v133
.LBB0_1898:
	s_or_b64 exec, exec, s[6:7]
	v_or_b32_e32 v142, 32, v167
	v_add_u32_e32 v138, s8, v142
	s_waitcnt lgkmcnt(0)
	v_ashrrev_i32_e32 v139, 31, v138
	v_lshlrev_b64 v[140:141], 11, v[138:139]
	v_lshl_add_u64 v[140:141], s[40:41], 0, v[140:141]
	v_lshl_add_u64 v[140:141], s[2:3], 1, v[140:141]
	v_lshl_add_u64 v[140:141], v[140:141], 0, s[0:1]
	v_mov_b32_e32 v133, 0
	v_lshl_add_u64 v[140:141], v[140:141], 0, v[132:133]
	s_waitcnt vmcnt(11)
	v_lshlrev_b32_e32 v140, 16, v204
	v_and_b32_e32 v141, 0xffff0000, v204
	v_lshlrev_b32_e32 v144, 16, v205
	v_and_b32_e32 v145, 0xffff0000, v205
	v_lshlrev_b32_e32 v152, 16, v206
	v_and_b32_e32 v153, 0xffff0000, v206
	s_waitcnt vmcnt(10)
	v_lshlrev_b32_e32 v154, 16, v208
	v_and_b32_e32 v155, 0xffff0000, v208
	v_lshlrev_b32_e32 v148, 16, v209
	v_and_b32_e32 v149, 0xffff0000, v209
	v_lshlrev_b32_e32 v146, 16, v207
	v_and_b32_e32 v147, 0xffff0000, v207
	v_lshlrev_b32_e32 v156, 16, v210
	v_and_b32_e32 v157, 0xffff0000, v210
	v_pk_fma_f32 v[96:97], v[96:97], 0.5, v[144:145] op_sel_hi:[1,0,1]
	v_pk_fma_f32 v[140:141], v[94:95], 0.5, v[140:141] op_sel_hi:[1,0,1]
	v_pk_fma_f32 v[94:95], v[90:91], 0.5, v[152:153] op_sel_hi:[1,0,1]
	v_pk_fma_f32 v[88:89], v[88:89], 0.5, v[148:149] op_sel_hi:[1,0,1]
	v_pk_fma_f32 v[90:91], v[86:87], 0.5, v[154:155] op_sel_hi:[1,0,1]
	v_lshlrev_b32_e32 v150, 16, v211
	v_and_b32_e32 v151, 0xffff0000, v211
	v_pk_fma_f32 v[92:93], v[92:93], 0.5, v[146:147] op_sel_hi:[1,0,1]
	v_pk_fma_f32 v[86:87], v[82:83], 0.5, v[156:157] op_sel_hi:[1,0,1]
	v_mul_f32_e32 v82, v141, v141
	v_mul_f32_e32 v83, v97, v97
	v_mul_f32_e32 v145, v91, v91
	v_mul_f32_e32 v146, v89, v89
	v_pk_fma_f32 v[84:85], v[84:85], 0.5, v[150:151] op_sel_hi:[1,0,1]
	v_mul_f32_e32 v143, v95, v95
	v_mul_f32_e32 v147, v87, v87
	v_fmac_f32_e32 v82, v140, v140
	v_fmac_f32_e32 v83, v96, v96
	v_fmac_f32_e32 v145, v90, v90
	v_fmac_f32_e32 v146, v88, v88
	v_mul_f32_e32 v144, v93, v93
	v_mul_f32_e32 v148, v85, v85
	v_fmac_f32_e32 v143, v94, v94
	v_fmac_f32_e32 v147, v86, v86
	v_add_f32_e32 v82, v82, v83
	v_add_f32_e32 v83, v145, v146
	v_fmac_f32_e32 v144, v92, v92
	v_fmac_f32_e32 v148, v84, v84
	v_add_f32_e32 v82, v143, v82
	v_add_f32_e32 v83, v147, v83
	v_add_f32_e32 v82, v144, v82
	v_add_f32_e32 v83, v148, v83
	v_add_f32_e32 v82, v82, v83
	v_mov_b32_e32 v83, v82
	s_nop 1
	v_permlane16_swap_b32_e32 v82, v83
	s_waitcnt lgkmcnt(0)
	v_add_f32_e32 v82, v82, v83
	v_mov_b32_e32 v83, v82
	s_nop 1
	v_permlane32_swap_b32_e32 v82, v83
	s_and_saveexec_b64 s[6:7], vcc
	s_cbranch_execz .LBB0_1900
	v_lshl_add_u32 v142, v142, 4, s9
	s_waitcnt lgkmcnt(0)
	v_add_f32_e32 v82, v82, v83
	ds_write_b32 v142, v82
; __device__ __forceinline__ void unpack8(const u32x4 w, f32x4& a, f32x4& b) { a = (f32x4){bflo(w.x), bfhi(w.x), bflo(w.y), bfhi(w.y)}; b = (f32x4){bflo(w.z), bfhi(w.z), bflo(w.w), bfhi(w.w)}; }
;     __device__ __forceinline__ void fused(Acc& acc, const Unit& u, int wr, int wc, int fr, int fq, LAS unsigned char* lds) const {
;     ...
; #pragma unroll
;         for (int ai = 0; ai < 2; ++ai)
; #pragma unroll
;             for (int m = 0; m < 4; ++m) {
;                 const int rt = ai * HALF + wr * 64 + m * 16 + fr; const int row = u.pm * BM + rt; float s = 0.f;
; #pragma unroll
;                 for (int bj = 0; bj < 2; ++bj) {
;                     const size_t off = (size_t)row * D + u.pn * BM + bj * HALF + wc * 32 + 8 * fq;
;                     f32x4 b0, b1; unpack8(*(const u32x4*)(base + off), b0, b1);
;                     const f32x4 v0 = b0 + acc[ai][bj][m][0] * scale, v1 = b1 + acc[ai][bj][m][1] * scale;
;                     acc[ai][bj][m][0] = v0; acc[ai][bj][m][1] = v1;
;                     s += (v0[0] * v0[0] + v0[1] * v0[1]) + (v0[2] * v0[2] + v0[3] * v0[3]) + (v1[0] * v1[0] + v1[1] * v1[1]) + (v1[2] * v1[2] + v1[3] * v1[3]);
;                 }
;                 s += __shfl_xor(s, 16); s += __shfl_xor(s, 32);
;                 if (fq == 0) Pw[rt * 4 + wc] = s;
.LBB0_1900:
	s_or_b64 exec, exec, s[6:7]
	v_or_b32_e32 v142, 48, v167
	v_add_u32_e32 v82, s8, v142
	s_waitcnt lgkmcnt(0)
	v_ashrrev_i32_e32 v83, 31, v82
	v_lshlrev_b64 v[144:145], 11, v[82:83]
	v_lshl_add_u64 v[144:145], s[40:41], 0, v[144:145]
	v_lshl_add_u64 v[144:145], s[2:3], 1, v[144:145]
	v_lshl_add_u64 v[144:145], v[144:145], 0, s[0:1]
	v_lshl_add_u64 v[148:149], v[144:145], 0, v[132:133]
	s_nop 0
	s_waitcnt vmcnt(9)
	v_lshlrev_b32_e32 v152, 16, v212
	v_and_b32_e32 v153, 0xffff0000, v212
	v_lshlrev_b32_e32 v144, 16, v213
	v_and_b32_e32 v145, 0xffff0000, v213
	s_waitcnt vmcnt(8)
	v_lshlrev_b32_e32 v156, 16, v216
	v_and_b32_e32 v157, 0xffff0000, v216
	v_lshlrev_b32_e32 v148, 16, v217
	v_and_b32_e32 v149, 0xffff0000, v217
	v_lshlrev_b32_e32 v154, 16, v214
	v_and_b32_e32 v155, 0xffff0000, v214
	v_lshlrev_b32_e32 v146, 16, v215
	v_and_b32_e32 v147, 0xffff0000, v215
	v_lshlrev_b32_e32 v158, 16, v218
	v_and_b32_e32 v159, 0xffff0000, v218
	v_pk_fma_f32 v[80:81], v[80:81], 0.5, v[144:145] op_sel_hi:[1,0,1]
	v_pk_fma_f32 v[78:79], v[78:79], 0.5, v[152:153] op_sel_hi:[1,0,1]
	v_pk_fma_f32 v[72:73], v[72:73], 0.5, v[148:149] op_sel_hi:[1,0,1]
	v_pk_fma_f32 v[70:71], v[70:71], 0.5, v[156:157] op_sel_hi:[1,0,1]
	v_lshlrev_b32_e32 v150, 16, v219
	v_and_b32_e32 v151, 0xffff0000, v219
	v_pk_fma_f32 v[76:77], v[76:77], 0.5, v[146:147] op_sel_hi:[1,0,1]
	v_pk_fma_f32 v[74:75], v[74:75], 0.5, v[154:155] op_sel_hi:[1,0,1]
	v_pk_fma_f32 v[66:67], v[66:67], 0.5, v[158:159] op_sel_hi:[1,0,1]
	v_mul_f32_e32 v133, v79, v79
	v_mul_f32_e32 v143, v81, v81
	v_mul_f32_e32 v146, v71, v71
	v_mul_f32_e32 v147, v73, v73
	v_pk_fma_f32 v[68:69], v[68:69], 0.5, v[150:151] op_sel_hi:[1,0,1]
	v_mul_f32_e32 v144, v75, v75
	v_mul_f32_e32 v148, v67, v67
	v_fmac_f32_e32 v133, v78, v78
	v_fmac_f32_e32 v143, v80, v80
	v_fmac_f32_e32 v146, v70, v70
	v_fmac_f32_e32 v147, v72, v72
	v_mul_f32_e32 v145, v77, v77
	v_mul_f32_e32 v149, v69, v69
	v_fmac_f32_e32 v144, v74, v74
	v_fmac_f32_e32 v148, v66, v66
	v_add_f32_e32 v133, v133, v143
	v_add_f32_e32 v143, v146, v147
	v_fmac_f32_e32 v145, v76, v76
	v_fmac_f32_e32 v149, v68, v68
	v_add_f32_e32 v133, v144, v133
	v_add_f32_e32 v143, v148, v143
	v_add_f32_e32 v133, v145, v133
	v_add_f32_e32 v143, v149, v143
	v_add_f32_e32 v133, v133, v143
	v_mov_b32_e32 v143, v133
	s_nop 1
	v_permlane16_swap_b32_e32 v133, v143
	s_waitcnt lgkmcnt(0)
	v_add_f32_e32 v133, v133, v143
	v_mov_b32_e32 v143, v133
	s_nop 1
	v_permlane32_swap_b32_e32 v133, v143
	s_and_saveexec_b64 s[6:7], vcc
	s_cbranch_execz .LBB0_1902
	v_lshl_add_u32 v142, v142, 4, s9
	s_waitcnt lgkmcnt(0)
	v_add_f32_e32 v133, v133, v143
	ds_write_b32 v142, v133
.LBB0_1902:
	s_or_b64 exec, exec, s[6:7]
	v_add_u32_e32 v144, 0x80, v167
	v_add_u32_e32 v142, s8, v144
	s_waitcnt lgkmcnt(0)
	v_ashrrev_i32_e32 v143, 31, v142
	v_lshlrev_b64 v[146:147], 11, v[142:143]
	v_lshl_add_u64 v[146:147], s[40:41], 0, v[146:147]
	v_lshl_add_u64 v[146:147], s[2:3], 1, v[146:147]
	v_lshl_add_u64 v[146:147], v[146:147], 0, s[0:1]
	v_mov_b32_e32 v133, 0
	v_lshl_add_u64 v[150:151], v[146:147], 0, v[132:133]
	s_nop 0
	s_waitcnt vmcnt(7)
	v_lshlrev_b32_e32 v154, 16, v220
	v_and_b32_e32 v155, 0xffff0000, v220
	v_lshlrev_b32_e32 v146, 16, v221
	v_and_b32_e32 v147, 0xffff0000, v221
	s_waitcnt vmcnt(6)
	v_lshlrev_b32_e32 v158, 16, v224
	v_and_b32_e32 v159, 0xffff0000, v224
	v_lshlrev_b32_e32 v150, 16, v225
	v_and_b32_e32 v151, 0xffff0000, v225
	v_lshlrev_b32_e32 v156, 16, v222
	v_and_b32_e32 v157, 0xffff0000, v222
	v_lshlrev_b32_e32 v148, 16, v223
	v_and_b32_e32 v149, 0xffff0000, v223
	v_lshlrev_b32_e32 v160, 16, v226
	v_and_b32_e32 v161, 0xffff0000, v226
	v_pk_fma_f32 v[64:65], v[64:65], 0.5, v[146:147] op_sel_hi:[1,0,1]
	v_pk_fma_f32 v[62:63], v[62:63], 0.5, v[154:155] op_sel_hi:[1,0,1]
	v_pk_fma_f32 v[56:57], v[56:57], 0.5, v[150:151] op_sel_hi:[1,0,1]
	v_pk_fma_f32 v[54:55], v[54:55], 0.5, v[158:159] op_sel_hi:[1,0,1]
	v_lshlrev_b32_e32 v152, 16, v227
	v_and_b32_e32 v153, 0xffff0000, v227
	v_pk_fma_f32 v[60:61], v[60:61], 0.5, v[148:149] op_sel_hi:[1,0,1]
	v_pk_fma_f32 v[58:59], v[58:59], 0.5, v[156:157] op_sel_hi:[1,0,1]
	v_pk_fma_f32 v[50:51], v[50:51], 0.5, v[160:161] op_sel_hi:[1,0,1]
	v_mul_f32_e32 v145, v63, v63
	v_mul_f32_e32 v146, v65, v65
	v_mul_f32_e32 v149, v55, v55
	v_mul_f32_e32 v150, v57, v57
	v_pk_fma_f32 v[52:53], v[52:53], 0.5, v[152:153] op_sel_hi:[1,0,1]
	v_mul_f32_e32 v147, v59, v59
	v_mul_f32_e32 v151, v51, v51
	v_fmac_f32_e32 v145, v62, v62
	v_fmac_f32_e32 v146, v64, v64
	v_fmac_f32_e32 v149, v54, v54
	v_fmac_f32_e32 v150, v56, v56
	v_mul_f32_e32 v148, v61, v61
	v_mul_f32_e32 v152, v53, v53
	v_fmac_f32_e32 v147, v58, v58
	v_fmac_f32_e32 v151, v50, v50
	v_add_f32_e32 v145, v145, v146
	v_add_f32_e32 v146, v149, v150
	v_fmac_f32_e32 v148, v60, v60
	v_fmac_f32_e32 v152, v52, v52
	v_add_f32_e32 v145, v147, v145
	v_add_f32_e32 v146, v151, v146
	v_add_f32_e32 v145, v148, v145
	v_add_f32_e32 v146, v152, v146
	v_add_f32_e32 v145, v145, v146
	v_mov_b32_e32 v146, v145
	s_nop 1
	v_permlane16_swap_b32_e32 v145, v146
	s_waitcnt lgkmcnt(0)
	v_add_f32_e32 v145, v145, v146
	v_mov_b32_e32 v146, v145
	s_nop 1
	v_permlane32_swap_b32_e32 v145, v146
	s_and_saveexec_b64 s[6:7], vcc
	s_cbranch_execz .LBB0_1904
	v_lshl_add_u32 v144, v144, 4, s9
	s_waitcnt lgkmcnt(0)
	v_add_f32_e32 v145, v145, v146
	ds_write_b32 v144, v145
; __device__ __forceinline__ void unpack8(const u32x4 w, f32x4& a, f32x4& b) { a = (f32x4){bflo(w.x), bfhi(w.x), bflo(w.y), bfhi(w.y)}; b = (f32x4){bflo(w.z), bfhi(w.z), bflo(w.w), bfhi(w.w)}; }
;     __device__ __forceinline__ void fused(Acc& acc, const Unit& u, int wr, int wc, int fr, int fq, LAS unsigned char* lds) const {
;     ...
; #pragma unroll
;         for (int ai = 0; ai < 2; ++ai)
; #pragma unroll
;             for (int m = 0; m < 4; ++m) {
;                 const int rt = ai * HALF + wr * 64 + m * 16 + fr; const int row = u.pm * BM + rt; float s = 0.f;
; #pragma unroll
;                 for (int bj = 0; bj < 2; ++bj) {
;                     const size_t off = (size_t)row * D + u.pn * BM + bj * HALF + wc * 32 + 8 * fq;
;                     f32x4 b0, b1; unpack8(*(const u32x4*)(base + off), b0, b1);
;                     const f32x4 v0 = b0 + acc[ai][bj][m][0] * scale, v1 = b1 + acc[ai][bj][m][1] * scale;
;                     acc[ai][bj][m][0] = v0; acc[ai][bj][m][1] = v1;
;                     s += (v0[0] * v0[0] + v0[1] * v0[1]) + (v0[2] * v0[2] + v0[3] * v0[3]) + (v1[0] * v1[0] + v1[1] * v1[1]) + (v1[2] * v1[2] + v1[3] * v1[3]);
;                 }
;                 s += __shfl_xor(s, 16); s += __shfl_xor(s, 32);
;                 if (fq == 0) Pw[rt * 4 + wc] = s;
.LBB0_1904:
	s_or_b64 exec, exec, s[6:7]
	s_waitcnt lgkmcnt(0)
	v_add_u32_e32 v146, 0x90, v167
	v_add_u32_e32 v144, s8, v146
	v_ashrrev_i32_e32 v145, 31, v144
	v_lshlrev_b64 v[148:149], 11, v[144:145]
	v_lshl_add_u64 v[148:149], s[40:41], 0, v[148:149]
	v_lshl_add_u64 v[148:149], s[2:3], 1, v[148:149]
	v_lshl_add_u64 v[148:149], v[148:149], 0, s[0:1]
	v_lshl_add_u64 v[152:153], v[148:149], 0, v[132:133]
	s_nop 0
	s_waitcnt vmcnt(5)
	v_lshlrev_b32_e32 v156, 16, v228
	v_and_b32_e32 v157, 0xffff0000, v228
	v_lshlrev_b32_e32 v148, 16, v229
	v_and_b32_e32 v149, 0xffff0000, v229
	s_waitcnt vmcnt(4)
	v_lshlrev_b32_e32 v160, 16, v232
	v_and_b32_e32 v161, 0xffff0000, v232
	v_lshlrev_b32_e32 v152, 16, v233
	v_and_b32_e32 v153, 0xffff0000, v233
	v_lshlrev_b32_e32 v158, 16, v230
	v_and_b32_e32 v159, 0xffff0000, v230
	v_lshlrev_b32_e32 v150, 16, v231
	v_and_b32_e32 v151, 0xffff0000, v231
	v_lshlrev_b32_e32 v162, 16, v234
	v_and_b32_e32 v163, 0xffff0000, v234
	v_pk_fma_f32 v[48:49], v[48:49], 0.5, v[148:149] op_sel_hi:[1,0,1]
	v_pk_fma_f32 v[46:47], v[46:47], 0.5, v[156:157] op_sel_hi:[1,0,1]
	v_pk_fma_f32 v[40:41], v[40:41], 0.5, v[152:153] op_sel_hi:[1,0,1]
	v_pk_fma_f32 v[38:39], v[38:39], 0.5, v[160:161] op_sel_hi:[1,0,1]
	v_lshlrev_b32_e32 v154, 16, v235
	v_and_b32_e32 v155, 0xffff0000, v235
	v_pk_fma_f32 v[44:45], v[44:45], 0.5, v[150:151] op_sel_hi:[1,0,1]
	v_pk_fma_f32 v[42:43], v[42:43], 0.5, v[158:159] op_sel_hi:[1,0,1]
	v_pk_fma_f32 v[34:35], v[34:35], 0.5, v[162:163] op_sel_hi:[1,0,1]
	v_mul_f32_e32 v133, v47, v47
	v_mul_f32_e32 v147, v49, v49
	v_mul_f32_e32 v150, v39, v39
	v_mul_f32_e32 v151, v41, v41
	v_pk_fma_f32 v[36:37], v[36:37], 0.5, v[154:155] op_sel_hi:[1,0,1]
	v_mul_f32_e32 v148, v43, v43
	v_mul_f32_e32 v152, v35, v35
	v_fmac_f32_e32 v133, v46, v46
	v_fmac_f32_e32 v147, v48, v48
	v_fmac_f32_e32 v150, v38, v38
	v_fmac_f32_e32 v151, v40, v40
	v_mul_f32_e32 v149, v45, v45
	v_mul_f32_e32 v153, v37, v37
	v_fmac_f32_e32 v148, v42, v42
	v_fmac_f32_e32 v152, v34, v34
	v_add_f32_e32 v133, v133, v147
	v_add_f32_e32 v147, v150, v151
	v_fmac_f32_e32 v149, v44, v44
	v_fmac_f32_e32 v153, v36, v36
	v_add_f32_e32 v133, v148, v133
	v_add_f32_e32 v147, v152, v147
	v_add_f32_e32 v133, v149, v133
	v_add_f32_e32 v147, v153, v147
	v_add_f32_e32 v133, v133, v147
	v_mov_b32_e32 v147, v133
	s_nop 1
	v_permlane16_swap_b32_e32 v133, v147
	s_waitcnt lgkmcnt(0)
	v_add_f32_e32 v133, v133, v147
	v_mov_b32_e32 v147, v133
	s_nop 1
	v_permlane32_swap_b32_e32 v133, v147
	s_and_saveexec_b64 s[6:7], vcc
	s_cbranch_execz .LBB0_1906
	v_lshl_add_u32 v146, v146, 4, s9
	s_waitcnt lgkmcnt(0)
	v_add_f32_e32 v133, v133, v147
	ds_write_b32 v146, v133
; __device__ __forceinline__ void unpack8(const u32x4 w, f32x4& a, f32x4& b) { a = (f32x4){bflo(w.x), bfhi(w.x), bflo(w.y), bfhi(w.y)}; b = (f32x4){bflo(w.z), bfhi(w.z), bflo(w.w), bfhi(w.w)}; }
;     __device__ __forceinline__ void fused(Acc& acc, const Unit& u, int wr, int wc, int fr, int fq, LAS unsigned char* lds) const {
;     ...
; #pragma unroll
;         for (int ai = 0; ai < 2; ++ai)
; #pragma unroll
;             for (int m = 0; m < 4; ++m) {
;                 const int rt = ai * HALF + wr * 64 + m * 16 + fr; const int row = u.pm * BM + rt; float s = 0.f;
; #pragma unroll
;                 for (int bj = 0; bj < 2; ++bj) {
;                     const size_t off = (size_t)row * D + u.pn * BM + bj * HALF + wc * 32 + 8 * fq;
;                     f32x4 b0, b1; unpack8(*(const u32x4*)(base + off), b0, b1);
;                     const f32x4 v0 = b0 + acc[ai][bj][m][0] * scale, v1 = b1 + acc[ai][bj][m][1] * scale;
;                     acc[ai][bj][m][0] = v0; acc[ai][bj][m][1] = v1;
;                     s += (v0[0] * v0[0] + v0[1] * v0[1]) + (v0[2] * v0[2] + v0[3] * v0[3]) + (v1[0] * v1[0] + v1[1] * v1[1]) + (v1[2] * v1[2] + v1[3] * v1[3]);
;                 }
;                 s += __shfl_xor(s, 16); s += __shfl_xor(s, 32);
;                 if (fq == 0) Pw[rt * 4 + wc] = s;
.LBB0_1906:
	s_or_b64 exec, exec, s[6:7]
	v_add_u32_e32 v148, 0xa0, v167
	v_add_u32_e32 v146, s8, v148
	s_waitcnt lgkmcnt(0)
	v_ashrrev_i32_e32 v147, 31, v146
	v_lshlrev_b64 v[150:151], 11, v[146:147]
	v_lshl_add_u64 v[150:151], s[40:41], 0, v[150:151]
	v_lshl_add_u64 v[150:151], s[2:3], 1, v[150:151]
	v_lshl_add_u64 v[150:151], v[150:151], 0, s[0:1]
	v_mov_b32_e32 v133, 0
	v_lshl_add_u64 v[154:155], v[150:151], 0, v[132:133]
	s_nop 0
	s_waitcnt vmcnt(3)
	v_lshlrev_b32_e32 v158, 16, v236
	v_and_b32_e32 v159, 0xffff0000, v236
	v_lshlrev_b32_e32 v150, 16, v237
	v_and_b32_e32 v151, 0xffff0000, v237
	s_waitcnt vmcnt(2)
	v_lshlrev_b32_e32 v162, 16, v240
	v_and_b32_e32 v163, 0xffff0000, v240
	v_lshlrev_b32_e32 v154, 16, v241
	v_and_b32_e32 v155, 0xffff0000, v241
	v_lshlrev_b32_e32 v160, 16, v238
	v_and_b32_e32 v161, 0xffff0000, v238
	v_lshlrev_b32_e32 v152, 16, v239
	v_and_b32_e32 v153, 0xffff0000, v239
	v_lshlrev_b32_e32 v170, 16, v242
	v_and_b32_e32 v171, 0xffff0000, v242
	v_pk_fma_f32 v[32:33], v[32:33], 0.5, v[150:151] op_sel_hi:[1,0,1]
	v_pk_fma_f32 v[30:31], v[30:31], 0.5, v[158:159] op_sel_hi:[1,0,1]
	v_pk_fma_f32 v[24:25], v[24:25], 0.5, v[154:155] op_sel_hi:[1,0,1]
	v_pk_fma_f32 v[22:23], v[22:23], 0.5, v[162:163] op_sel_hi:[1,0,1]
	v_lshlrev_b32_e32 v156, 16, v243
	v_and_b32_e32 v157, 0xffff0000, v243
	v_pk_fma_f32 v[28:29], v[28:29], 0.5, v[152:153] op_sel_hi:[1,0,1]
	v_pk_fma_f32 v[26:27], v[26:27], 0.5, v[160:161] op_sel_hi:[1,0,1]
	v_pk_fma_f32 v[18:19], v[18:19], 0.5, v[170:171] op_sel_hi:[1,0,1]
	v_mul_f32_e32 v149, v31, v31
	v_mul_f32_e32 v150, v33, v33
	v_mul_f32_e32 v153, v23, v23
	v_mul_f32_e32 v154, v25, v25
	v_pk_fma_f32 v[20:21], v[20:21], 0.5, v[156:157] op_sel_hi:[1,0,1]
	v_mul_f32_e32 v151, v27, v27
	v_mul_f32_e32 v155, v19, v19
	v_fmac_f32_e32 v149, v30, v30
	v_fmac_f32_e32 v150, v32, v32
	v_fmac_f32_e32 v153, v22, v22
	v_fmac_f32_e32 v154, v24, v24
	v_mul_f32_e32 v152, v29, v29
	v_mul_f32_e32 v156, v21, v21
	v_fmac_f32_e32 v151, v26, v26
	v_fmac_f32_e32 v155, v18, v18
	v_add_f32_e32 v149, v149, v150
	v_add_f32_e32 v150, v153, v154
	v_fmac_f32_e32 v152, v28, v28
	v_fmac_f32_e32 v156, v20, v20
	v_add_f32_e32 v149, v151, v149
	v_add_f32_e32 v150, v155, v150
	v_add_f32_e32 v149, v152, v149
	v_add_f32_e32 v150, v156, v150
	v_add_f32_e32 v149, v149, v150
	v_mov_b32_e32 v150, v149
	s_nop 1
	v_permlane16_swap_b32_e32 v149, v150
	s_waitcnt lgkmcnt(0)
	v_add_f32_e32 v149, v149, v150
	v_mov_b32_e32 v150, v149
	s_nop 1
	v_permlane32_swap_b32_e32 v149, v150
	s_and_saveexec_b64 s[6:7], vcc
	s_cbranch_execz .LBB0_1908
	v_lshl_add_u32 v148, v148, 4, s9
	s_waitcnt lgkmcnt(0)
	v_add_f32_e32 v149, v149, v150
	ds_write_b32 v148, v149
.LBB0_1908:
	s_or_b64 exec, exec, s[6:7]
	v_add_u32_e32 v169, 0xb0, v167
	v_add_u32_e32 v148, s8, v169
	v_ashrrev_i32_e32 v149, 31, v148
	s_waitcnt lgkmcnt(0)
	v_lshlrev_b64 v[150:151], 11, v[148:149]
	v_lshl_add_u64 v[150:151], s[40:41], 0, v[150:151]
	v_lshl_add_u64 v[150:151], s[2:3], 1, v[150:151]
	v_lshl_add_u64 v[150:151], v[150:151], 0, s[0:1]
	v_lshl_add_u64 v[132:133], v[150:151], 0, v[132:133]
	s_waitcnt vmcnt(1)
	v_lshlrev_b32_e32 v132, 16, v244
	v_and_b32_e32 v133, 0xffff0000, v244
	v_lshlrev_b32_e32 v150, 16, v245
	v_and_b32_e32 v151, 0xffff0000, v245
	s_waitcnt vmcnt(0)
	v_lshlrev_b32_e32 v170, 16, v248
	v_and_b32_e32 v171, 0xffff0000, v248
	v_lshlrev_b32_e32 v172, 16, v249
	v_and_b32_e32 v173, 0xffff0000, v249
	v_lshlrev_b32_e32 v158, 16, v246
	v_and_b32_e32 v159, 0xffff0000, v246
	v_lshlrev_b32_e32 v152, 16, v247
	v_and_b32_e32 v153, 0xffff0000, v247
	v_lshlrev_b32_e32 v174, 16, v250
	v_and_b32_e32 v175, 0xffff0000, v250
	v_lshlrev_b32_e32 v176, 16, v251
	v_and_b32_e32 v177, 0xffff0000, v251
	v_pk_fma_f32 v[160:161], v[16:17], 0.5, v[150:151] op_sel_hi:[1,0,1]
	v_pk_fma_f32 v[162:163], v[14:15], 0.5, v[132:133] op_sel_hi:[1,0,1]
	v_pk_fma_f32 v[150:151], v[8:9], 0.5, v[172:173] op_sel_hi:[1,0,1]
	v_pk_fma_f32 v[156:157], v[6:7], 0.5, v[170:171] op_sel_hi:[1,0,1]
	v_pk_fma_f32 v[154:155], v[12:13], 0.5, v[152:153] op_sel_hi:[1,0,1]
	v_pk_fma_f32 v[158:159], v[10:11], 0.5, v[158:159] op_sel_hi:[1,0,1]
	v_pk_fma_f32 v[152:153], v[2:3], 0.5, v[174:175] op_sel_hi:[1,0,1]
	v_mul_f32_e32 v2, v163, v163
	v_mul_f32_e32 v3, v161, v161
	v_mul_f32_e32 v6, v157, v157
	v_mul_f32_e32 v7, v151, v151
	v_pk_fma_f32 v[132:133], v[4:5], 0.5, v[176:177] op_sel_hi:[1,0,1]
	v_mul_f32_e32 v4, v159, v159
	v_mul_f32_e32 v8, v153, v153
	v_fmac_f32_e32 v2, v162, v162
	v_fmac_f32_e32 v3, v160, v160
	v_fmac_f32_e32 v6, v156, v156
	v_fmac_f32_e32 v7, v150, v150
	v_mul_f32_e32 v5, v155, v155
	v_mul_f32_e32 v9, v133, v133
	v_fmac_f32_e32 v4, v158, v158
	v_fmac_f32_e32 v8, v152, v152
	v_add_f32_e32 v2, v2, v3
	v_add_f32_e32 v3, v6, v7
	v_fmac_f32_e32 v5, v154, v154
	v_fmac_f32_e32 v9, v132, v132
	v_add_f32_e32 v2, v4, v2
	v_add_f32_e32 v3, v8, v3
	v_add_f32_e32 v2, v5, v2
	v_add_f32_e32 v3, v9, v3
	v_add_f32_e32 v2, v2, v3
	v_mov_b32_e32 v3, v2
	s_nop 1
	v_permlane16_swap_b32_e32 v2, v3
	s_waitcnt lgkmcnt(0)
	v_add_f32_e32 v2, v2, v3
	v_mov_b32_e32 v3, v2
	s_nop 1
	v_permlane32_swap_b32_e32 v2, v3
	s_and_saveexec_b64 s[0:1], vcc
	s_cbranch_execz .LBB0_1910
	v_lshl_add_u32 v4, v169, 4, s9
	s_waitcnt lgkmcnt(0)
	v_add_f32_e32 v2, v2, v3
	ds_write_b32 v4, v2
